# fused LayerNorm epilogues: dequantisation-vector loads share the residual staging wait (their own round trip removed), 3 variants
# speedup vs baseline: 1.0077x; 1.0056x over previous
.LBB0_415:
	s_lshl_b32 s0, s3, 10
	s_lshl_b64 s[8:9], s[0:1], 2
	v_readlane_b32 s3, v253, 4
	s_add_u32 s8, s3, s8
	v_readlane_b32 s3, v253, 5
	s_addc_u32 s9, s3, s9
	v_lshl_add_u64 v[20:21], v[160:161], 2, s[8:9]
	global_load_dwordx4 v[196:199], v[20:21], off
	global_load_dwordx4 v[200:203], v[20:21], off offset:64
	global_load_dwordx4 v[204:207], v[20:21], off offset:512
	global_load_dwordx4 v[208:211], v[20:21], off offset:576
	s_mov_b32 s8, 0x3a800000
	s_lshl_b32 s10, s23, 5
	v_readlane_b32 s3, v254, 17
	s_add_i32 s3, s3, s10
	s_lshl_b32 s11, s34, 2
	v_cmp_gt_u32_e32 vcc, 16, v178
	v_mbcnt_lo_u32_b32 v30, -1, 0
	v_mbcnt_hi_u32_b32 v30, -1, v30
	v_ashrrev_i32_e32 v31, 5, v30
	v_add_u32_e32 v16, s3, v31
	v_and_b32_e32 v180, 31, v30
	v_ashrrev_i32_e32 v17, 31, v16
	v_readlane_b32 s8, v253, 47
	v_lshlrev_b64 v[16:17], 11, v[16:17]
	v_readlane_b32 s9, v253, 48
	s_lshl_b32 s3, s23, 14
	v_bitop3_b32 v18, v31, v180, 15 bitop3:0x6c
	v_lshl_add_u64 v[16:17], s[8:9], 0, v[16:17]
	s_add_i32 s3, s3, 0
	v_lshlrev_b32_e32 v230, 4, v18
	v_lshl_add_u64 v[18:19], v[16:17], 0, v[230:231]
	s_mov_b32 m0, s3
	s_mov_b64 s[8:9], 0x1000
	global_load_lds_dwordx4 v[18:19], off
	v_lshl_add_u64 v[18:19], v[16:17], 0, s[8:9]
	v_add_u32_e32 v16, 2, v31
	v_bitop3_b32 v16, v16, v180, 15 bitop3:0x6c
	v_lshlrev_b32_e32 v16, 4, v16
	v_mov_b32_e32 v17, v231
	s_add_i32 m0, s3, 0x400
	v_lshl_add_u64 v[20:21], v[18:19], 0, v[16:17]
	global_load_lds_dwordx4 v[20:21], off
	v_lshl_add_u64 v[20:21], v[18:19], 0, s[8:9]
	v_add_u32_e32 v18, 4, v31
	v_bitop3_b32 v18, v18, v180, 15 bitop3:0x6c
	v_lshlrev_b32_e32 v18, 4, v18
	v_mov_b32_e32 v19, v231
	s_add_i32 m0, s3, 0x800
	v_lshl_add_u64 v[22:23], v[20:21], 0, v[18:19]
	global_load_lds_dwordx4 v[22:23], off
	v_lshl_add_u64 v[22:23], v[20:21], 0, s[8:9]
	v_add_u32_e32 v20, 6, v31
	v_bitop3_b32 v20, v20, v180, 15 bitop3:0x6c
	v_lshlrev_b32_e32 v20, 4, v20
	v_mov_b32_e32 v21, v231
	s_add_i32 m0, s3, 0xc00
	v_lshl_add_u64 v[24:25], v[22:23], 0, v[20:21]
	global_load_lds_dwordx4 v[24:25], off
	v_lshl_add_u64 v[24:25], v[22:23], 0, s[8:9]
	v_xor_b32_e32 v22, 0x80, v230
	v_mov_b32_e32 v23, v231
	s_add_i32 m0, s3, 0x1000
	v_lshl_add_u64 v[26:27], v[24:25], 0, v[22:23]
	global_load_lds_dwordx4 v[26:27], off
	v_lshl_add_u64 v[26:27], v[24:25], 0, s[8:9]
	v_add_u32_e32 v24, 10, v31
	v_bitop3_b32 v24, v24, v180, 15 bitop3:0x6c
	v_lshlrev_b32_e32 v24, 4, v24
	v_mov_b32_e32 v25, v231
	s_add_i32 m0, s3, 0x1400
	v_lshl_add_u64 v[28:29], v[26:27], 0, v[24:25]
	global_load_lds_dwordx4 v[28:29], off
	v_add_u32_e32 v28, 12, v31
	v_lshl_add_u64 v[26:27], v[26:27], 0, s[8:9]
	v_bitop3_b32 v28, v28, v180, 15 bitop3:0x6c
	v_lshlrev_b32_e32 v28, 4, v28
	v_mov_b32_e32 v29, v231
	v_add_u32_e32 v181, 14, v31
	v_lshl_add_u64 v[182:183], v[26:27], 0, v[28:29]
	s_add_i32 m0, s3, 0x1800
	v_lshl_add_u64 v[26:27], v[26:27], 0, s[8:9]
	v_bitop3_b32 v180, v181, v180, 15 bitop3:0x6c
	global_load_lds_dwordx4 v[182:183], off
	v_lshlrev_b32_e32 v180, 4, v180
	v_mov_b32_e32 v181, v231
	v_lshl_add_u64 v[182:183], v[26:27], 0, v[180:181]
	s_add_i32 m0, s3, 0x1c00
	v_lshl_add_u64 v[26:27], v[26:27], 0, s[8:9]
	global_load_lds_dwordx4 v[182:183], off
	s_add_i32 m0, s3, 0x2000
	v_lshl_add_u64 v[182:183], v[26:27], 0, v[230:231]
	v_lshl_add_u64 v[26:27], v[26:27], 0, s[8:9]
	global_load_lds_dwordx4 v[182:183], off
	s_add_i32 m0, s3, 0x2400
	v_lshl_add_u64 v[16:17], v[26:27], 0, v[16:17]
	global_load_lds_dwordx4 v[16:17], off
	v_lshl_add_u64 v[16:17], v[26:27], 0, s[8:9]
	s_add_i32 m0, s3, 0x2800
	v_lshl_add_u64 v[18:19], v[16:17], 0, v[18:19]
	v_lshl_add_u64 v[16:17], v[16:17], 0, s[8:9]
	global_load_lds_dwordx4 v[18:19], off
	s_add_i32 m0, s3, 0x2c00
	v_lshl_add_u64 v[18:19], v[16:17], 0, v[20:21]
	v_lshl_add_u64 v[16:17], v[16:17], 0, s[8:9]
	global_load_lds_dwordx4 v[18:19], off
	s_add_i32 m0, s3, 0x3000
	v_lshl_add_u64 v[18:19], v[16:17], 0, v[22:23]
	v_lshl_add_u64 v[16:17], v[16:17], 0, s[8:9]
	global_load_lds_dwordx4 v[18:19], off
	s_add_i32 m0, s3, 0x3400
	v_lshl_add_u64 v[18:19], v[16:17], 0, v[24:25]
	v_lshl_add_u64 v[16:17], v[16:17], 0, s[8:9]
	global_load_lds_dwordx4 v[18:19], off
	s_add_i32 m0, s3, 0x3800
	v_lshl_add_u64 v[18:19], v[16:17], 0, v[28:29]
	v_lshl_add_u64 v[16:17], v[16:17], 0, s[8:9]
	global_load_lds_dwordx4 v[18:19], off
	s_add_i32 m0, s3, 0x3c00
	v_lshl_add_u64 v[18:19], v[16:17], 0, v[180:181]
	v_lshl_add_u64 v[16:17], v[16:17], 0, s[8:9]
	global_load_lds_dwordx4 v[18:19], off
	v_lshrrev_b32_e32 v18, 1, v30
	v_lshlrev_b32_e32 v17, 9, v30
	v_and_b32_e32 v17, 0x200, v17
	v_and_b32_e32 v18, 8, v18
	v_add_u32_e32 v28, s11, v31
	v_and_b32_e32 v16, 15, v30
	v_add3_u32 v183, 0, v17, v18
	v_add_u32_e32 v17, 16, v28
	v_bitop3_b32 v17, v17, v30, 15 bitop3:0x78
	s_lshl_b32 s3, s22, 15
	v_lshlrev_b32_e32 v16, 9, v16
	v_lshlrev_b32_e32 v180, 4, v17
	v_or_b32_e32 v184, s3, v16
	v_mov_b32_e32 v17, s3
	s_movk_i32 s3, 0x9c00
	v_bitop3_b32 v16, v16, s3, v17 bitop3:0xc8
	v_add_u32_e32 v181, v183, v16
	v_bitop3_b32 v16, v28, v30, 15 bitop3:0x78
	v_lshlrev_b32_e32 v182, 4, v16
	s_waitcnt vmcnt(0)
	s_mov_b32 s100, 0x3a800000
	v_pk_mul_f32 v[174:175], v[196:197], s[100:101] op_sel_hi:[1,0]
	v_pk_mul_f32 v[176:177], v[198:199], s[100:101] op_sel_hi:[1,0]
	v_pk_mul_f32 v[170:171], v[200:201], s[100:101] op_sel_hi:[1,0]
	v_pk_mul_f32 v[172:173], v[202:203], s[100:101] op_sel_hi:[1,0]
	v_pk_mul_f32 v[166:167], v[204:205], s[100:101] op_sel_hi:[1,0]
	v_pk_mul_f32 v[168:169], v[206:207], s[100:101] op_sel_hi:[1,0]
	v_pk_mul_f32 v[162:163], v[208:209], s[100:101] op_sel_hi:[1,0]
	v_pk_mul_f32 v[164:165], v[210:211], s[100:101] op_sel_hi:[1,0]
	s_barrier
	v_add_u32_e32 v185, v181, v182
	ds_read_b64 v[16:17], v185
	s_mov_b32 s8, 0x3fd744fd
	s_lshl_b32 s3, s34, 3
	s_add_i32 s12, s3, 0
	s_waitcnt lgkmcnt(0)
	v_cvt_f32_f16_e32 v18, v16
	v_cvt_f32_f16_sdwa v19, v16 dst_sel:DWORD dst_unused:UNUSED_PAD src0_sel:WORD_1
	v_cvt_f32_f16_e32 v16, v17
	v_cvt_f32_f16_sdwa v17, v17 dst_sel:DWORD dst_unused:UNUSED_PAD src0_sel:WORD_1
	v_pk_mul_f32 v[20:21], v[18:19], s[8:9] op_sel_hi:[1,0]
	v_pk_mul_f32 v[16:17], v[16:17], s[8:9] op_sel_hi:[1,0]
	s_nop 0
	v_pk_fma_f32 v[18:19], v[158:159], v[176:177], v[16:17]
	v_pk_fma_f32 v[16:17], v[156:157], v[174:175], v[20:21]
	v_add_u32_e32 v20, 2, v28
	v_bitop3_b32 v20, v20, v30, 15 bitop3:0x78
	v_lshlrev_b32_e32 v156, 4, v20
	v_add_u32_e32 v157, v181, v156
	ds_read_b64 v[20:21], v157
	s_waitcnt lgkmcnt(0)
	v_cvt_f32_f16_e32 v22, v20
	v_cvt_f32_f16_sdwa v23, v20 dst_sel:DWORD dst_unused:UNUSED_PAD src0_sel:WORD_1
	v_cvt_f32_f16_e32 v20, v21
	v_cvt_f32_f16_sdwa v21, v21 dst_sel:DWORD dst_unused:UNUSED_PAD src0_sel:WORD_1
	v_pk_mul_f32 v[22:23], v[22:23], s[8:9] op_sel_hi:[1,0]
	s_nop 0
	v_pk_fma_f32 v[24:25], v[152:153], v[170:171], v[22:23]
	v_pk_mul_f32 v[20:21], v[20:21], s[8:9] op_sel_hi:[1,0]
	v_add_u32_e32 v153, v181, v180
	v_pk_fma_f32 v[26:27], v[154:155], v[172:173], v[20:21]
	ds_read_b64 v[20:21], v153
	s_waitcnt lgkmcnt(0)
	v_cvt_f32_f16_e32 v22, v20
	v_cvt_f32_f16_sdwa v23, v20 dst_sel:DWORD dst_unused:UNUSED_PAD src0_sel:WORD_1
	v_cvt_f32_f16_e32 v20, v21
	v_cvt_f32_f16_sdwa v21, v21 dst_sel:DWORD dst_unused:UNUSED_PAD src0_sel:WORD_1
	v_pk_mul_f32 v[22:23], v[22:23], s[8:9] op_sel_hi:[1,0]
	s_nop 0
	v_pk_fma_f32 v[148:149], v[148:149], v[166:167], v[22:23]
	v_pk_mul_f32 v[20:21], v[20:21], s[8:9] op_sel_hi:[1,0]
	s_nop 0
	v_pk_fma_f32 v[150:151], v[150:151], v[168:169], v[20:21]
	v_add_u32_e32 v20, 18, v28
	v_bitop3_b32 v20, v20, v30, 15 bitop3:0x78
	v_lshlrev_b32_e32 v152, 4, v20
	v_add_u32_e32 v154, v181, v152
	ds_read_b64 v[20:21], v154
	s_waitcnt lgkmcnt(0)
	v_cvt_f32_f16_e32 v22, v20
	v_cvt_f32_f16_sdwa v23, v20 dst_sel:DWORD dst_unused:UNUSED_PAD src0_sel:WORD_1
	v_cvt_f32_f16_e32 v20, v21
	v_cvt_f32_f16_sdwa v21, v21 dst_sel:DWORD dst_unused:UNUSED_PAD src0_sel:WORD_1
	v_pk_mul_f32 v[22:23], v[22:23], s[8:9] op_sel_hi:[1,0]
	s_nop 0
	v_pk_fma_f32 v[144:145], v[144:145], v[162:163], v[22:23]
	v_pk_mul_f32 v[20:21], v[20:21], s[8:9] op_sel_hi:[1,0]
	s_nop 0
	v_pk_fma_f32 v[146:147], v[146:147], v[164:165], v[20:21]
	s_nop 0
	ds_read_b64 v[20:21], v185 offset:8192
	s_waitcnt lgkmcnt(0)
	v_cvt_f32_f16_e32 v22, v20
	v_cvt_f32_f16_sdwa v23, v20 dst_sel:DWORD dst_unused:UNUSED_PAD src0_sel:WORD_1
	v_cvt_f32_f16_e32 v20, v21
	v_cvt_f32_f16_sdwa v21, v21 dst_sel:DWORD dst_unused:UNUSED_PAD src0_sel:WORD_1
	v_pk_mul_f32 v[28:29], v[22:23], s[8:9] op_sel_hi:[1,0]
	v_pk_mul_f32 v[20:21], v[20:21], s[8:9] op_sel_hi:[1,0]
	s_nop 0
	v_pk_fma_f32 v[22:23], v[142:143], v[176:177], v[20:21]
	v_pk_fma_f32 v[20:21], v[140:141], v[174:175], v[28:29]
	ds_read_b64 v[28:29], v157 offset:8192
	v_pk_add_f32 v[142:143], v[0:1], v[24:25]
	v_lshlrev_b32_e32 v24, 2, v178
	s_waitcnt lgkmcnt(0)
	v_cvt_f32_f16_e32 v30, v28
	v_cvt_f32_f16_sdwa v31, v28 dst_sel:DWORD dst_unused:UNUSED_PAD src0_sel:WORD_1
	v_cvt_f32_f16_e32 v28, v29
	v_cvt_f32_f16_sdwa v29, v29 dst_sel:DWORD dst_unused:UNUSED_PAD src0_sel:WORD_1
	v_pk_mul_f32 v[140:141], v[30:31], s[8:9] op_sel_hi:[1,0]
	v_pk_mul_f32 v[28:29], v[28:29], s[8:9] op_sel_hi:[1,0]
	s_nop 0
	v_pk_fma_f32 v[30:31], v[138:139], v[172:173], v[28:29]
	v_pk_fma_f32 v[28:29], v[136:137], v[170:171], v[140:141]
	ds_read_b64 v[136:137], v153 offset:8192
	v_add_u32_e32 v140, 0x10000, v181
	s_waitcnt lgkmcnt(0)
	v_cvt_f32_f16_e32 v138, v136
	v_cvt_f32_f16_sdwa v139, v136 dst_sel:DWORD dst_unused:UNUSED_PAD src0_sel:WORD_1
	v_cvt_f32_f16_e32 v136, v137
	v_cvt_f32_f16_sdwa v137, v137 dst_sel:DWORD dst_unused:UNUSED_PAD src0_sel:WORD_1
	v_pk_mul_f32 v[138:139], v[138:139], s[8:9] op_sel_hi:[1,0]
	s_nop 0
	v_pk_fma_f32 v[132:133], v[132:133], v[166:167], v[138:139]
	v_pk_mul_f32 v[136:137], v[136:137], s[8:9] op_sel_hi:[1,0]
	s_nop 0
	v_pk_fma_f32 v[134:135], v[134:135], v[168:169], v[136:137]
	ds_read_b64 v[136:137], v154 offset:8192
	s_waitcnt lgkmcnt(0)
	v_cvt_f32_f16_e32 v138, v136
	v_cvt_f32_f16_sdwa v139, v136 dst_sel:DWORD dst_unused:UNUSED_PAD src0_sel:WORD_1
	v_cvt_f32_f16_e32 v136, v137
	v_cvt_f32_f16_sdwa v137, v137 dst_sel:DWORD dst_unused:UNUSED_PAD src0_sel:WORD_1
	v_pk_mul_f32 v[138:139], v[138:139], s[8:9] op_sel_hi:[1,0]
	s_nop 0
	v_pk_fma_f32 v[128:129], v[128:129], v[162:163], v[138:139]
	v_pk_mul_f32 v[136:137], v[136:137], s[8:9] op_sel_hi:[1,0]
	s_nop 0
	v_pk_fma_f32 v[130:131], v[130:131], v[164:165], v[136:137]
	s_nop 0
	ds_read_b64 v[136:137], v185 offset:16384
	s_waitcnt lgkmcnt(0)
	v_cvt_f32_f16_e32 v138, v136
	v_cvt_f32_f16_sdwa v139, v136 dst_sel:DWORD dst_unused:UNUSED_PAD src0_sel:WORD_1
	v_cvt_f32_f16_e32 v136, v137
	v_cvt_f32_f16_sdwa v137, v137 dst_sel:DWORD dst_unused:UNUSED_PAD src0_sel:WORD_1
	v_pk_mul_f32 v[138:139], v[138:139], s[8:9] op_sel_hi:[1,0]
	s_nop 0
	v_pk_fma_f32 v[124:125], v[124:125], v[174:175], v[138:139]
	v_pk_mul_f32 v[136:137], v[136:137], s[8:9] op_sel_hi:[1,0]
	s_nop 0
	v_pk_fma_f32 v[126:127], v[126:127], v[176:177], v[136:137]
	ds_read_b64 v[136:137], v157 offset:16384
	s_waitcnt lgkmcnt(0)
	v_cvt_f32_f16_e32 v138, v136
	v_cvt_f32_f16_sdwa v139, v136 dst_sel:DWORD dst_unused:UNUSED_PAD src0_sel:WORD_1
	v_cvt_f32_f16_e32 v136, v137
	v_cvt_f32_f16_sdwa v137, v137 dst_sel:DWORD dst_unused:UNUSED_PAD src0_sel:WORD_1
	v_pk_mul_f32 v[138:139], v[138:139], s[8:9] op_sel_hi:[1,0]
	s_nop 0
	v_pk_fma_f32 v[120:121], v[120:121], v[170:171], v[138:139]
	v_pk_mul_f32 v[136:137], v[136:137], s[8:9] op_sel_hi:[1,0]
	s_nop 0
	v_pk_fma_f32 v[122:123], v[122:123], v[172:173], v[136:137]
	ds_read_b64 v[136:137], v153 offset:16384
	s_waitcnt lgkmcnt(0)
	v_cvt_f32_f16_e32 v138, v136
	v_cvt_f32_f16_sdwa v139, v136 dst_sel:DWORD dst_unused:UNUSED_PAD src0_sel:WORD_1
	v_cvt_f32_f16_e32 v136, v137
	v_cvt_f32_f16_sdwa v137, v137 dst_sel:DWORD dst_unused:UNUSED_PAD src0_sel:WORD_1
	v_pk_mul_f32 v[138:139], v[138:139], s[8:9] op_sel_hi:[1,0]
	s_nop 0
	v_pk_fma_f32 v[116:117], v[116:117], v[166:167], v[138:139]
	v_pk_mul_f32 v[136:137], v[136:137], s[8:9] op_sel_hi:[1,0]
	s_nop 0
	v_pk_fma_f32 v[118:119], v[118:119], v[168:169], v[136:137]
	ds_read_b64 v[136:137], v154 offset:16384
	s_waitcnt lgkmcnt(0)
	v_cvt_f32_f16_e32 v138, v136
	v_cvt_f32_f16_sdwa v139, v136 dst_sel:DWORD dst_unused:UNUSED_PAD src0_sel:WORD_1
	v_cvt_f32_f16_e32 v136, v137
	v_cvt_f32_f16_sdwa v137, v137 dst_sel:DWORD dst_unused:UNUSED_PAD src0_sel:WORD_1
	v_pk_mul_f32 v[138:139], v[138:139], s[8:9] op_sel_hi:[1,0]
	s_nop 0
	v_pk_fma_f32 v[112:113], v[112:113], v[162:163], v[138:139]
	v_pk_mul_f32 v[136:137], v[136:137], s[8:9] op_sel_hi:[1,0]
	s_nop 0
	v_pk_fma_f32 v[114:115], v[114:115], v[164:165], v[136:137]
	s_nop 0
	ds_read_b64 v[136:137], v185 offset:24576
	s_waitcnt lgkmcnt(0)
	v_cvt_f32_f16_e32 v138, v136
	v_cvt_f32_f16_sdwa v139, v136 dst_sel:DWORD dst_unused:UNUSED_PAD src0_sel:WORD_1
	v_cvt_f32_f16_e32 v136, v137
	v_cvt_f32_f16_sdwa v137, v137 dst_sel:DWORD dst_unused:UNUSED_PAD src0_sel:WORD_1
	v_pk_mul_f32 v[138:139], v[138:139], s[8:9] op_sel_hi:[1,0]
	s_nop 0
	v_pk_fma_f32 v[108:109], v[108:109], v[174:175], v[138:139]
	v_pk_mul_f32 v[136:137], v[136:137], s[8:9] op_sel_hi:[1,0]
	s_nop 0
	v_pk_fma_f32 v[110:111], v[110:111], v[176:177], v[136:137]
	ds_read_b64 v[136:137], v157 offset:24576
	v_xor_b32_e32 v157, 64, v24
	s_waitcnt lgkmcnt(0)
	v_cvt_f32_f16_e32 v138, v136
	v_cvt_f32_f16_sdwa v139, v136 dst_sel:DWORD dst_unused:UNUSED_PAD src0_sel:WORD_1
	v_cvt_f32_f16_e32 v136, v137
	v_cvt_f32_f16_sdwa v137, v137 dst_sel:DWORD dst_unused:UNUSED_PAD src0_sel:WORD_1
	v_pk_mul_f32 v[138:139], v[138:139], s[8:9] op_sel_hi:[1,0]
	s_nop 0
	v_pk_fma_f32 v[104:105], v[104:105], v[170:171], v[138:139]
	v_pk_mul_f32 v[136:137], v[136:137], s[8:9] op_sel_hi:[1,0]
	s_nop 0
	v_pk_fma_f32 v[106:107], v[106:107], v[172:173], v[136:137]
	ds_read_b64 v[136:137], v153 offset:24576
	s_waitcnt lgkmcnt(0)
	v_cvt_f32_f16_e32 v138, v136
	v_cvt_f32_f16_sdwa v139, v136 dst_sel:DWORD dst_unused:UNUSED_PAD src0_sel:WORD_1
	v_cvt_f32_f16_e32 v136, v137
	v_cvt_f32_f16_sdwa v137, v137 dst_sel:DWORD dst_unused:UNUSED_PAD src0_sel:WORD_1
	v_pk_mul_f32 v[138:139], v[138:139], s[8:9] op_sel_hi:[1,0]
	s_nop 0
	v_pk_fma_f32 v[100:101], v[100:101], v[166:167], v[138:139]
	v_pk_mul_f32 v[136:137], v[136:137], s[8:9] op_sel_hi:[1,0]
	s_nop 0
	v_pk_fma_f32 v[102:103], v[102:103], v[168:169], v[136:137]
	ds_read_b64 v[136:137], v154 offset:24576
	v_pk_add_f32 v[154:155], v[4:5], v[16:17]
	v_pk_add_f32 v[16:17], v[10:11], v[146:147]
	s_waitcnt lgkmcnt(0)
	v_cvt_f32_f16_e32 v138, v136
	v_cvt_f32_f16_sdwa v139, v136 dst_sel:DWORD dst_unused:UNUSED_PAD src0_sel:WORD_1
	v_cvt_f32_f16_e32 v136, v137
	v_cvt_f32_f16_sdwa v137, v137 dst_sel:DWORD dst_unused:UNUSED_PAD src0_sel:WORD_1
	v_pk_mul_f32 v[138:139], v[138:139], s[8:9] op_sel_hi:[1,0]
	s_nop 0
	v_pk_fma_f32 v[96:97], v[96:97], v[162:163], v[138:139]
	v_pk_mul_f32 v[136:137], v[136:137], s[8:9] op_sel_hi:[1,0]
	s_nop 0
	v_pk_fma_f32 v[98:99], v[98:99], v[164:165], v[136:137]
	v_add_u32_e32 v136, v140, v182
	ds_read_b64 v[136:137], v136
	s_waitcnt lgkmcnt(0)
	v_cvt_f32_f16_e32 v138, v136
	v_cvt_f32_f16_sdwa v139, v136 dst_sel:DWORD dst_unused:UNUSED_PAD src0_sel:WORD_1
	v_cvt_f32_f16_e32 v136, v137
	v_cvt_f32_f16_sdwa v137, v137 dst_sel:DWORD dst_unused:UNUSED_PAD src0_sel:WORD_1
	v_pk_mul_f32 v[138:139], v[138:139], s[8:9] op_sel_hi:[1,0]
	s_nop 0
	v_pk_fma_f32 v[92:93], v[92:93], v[174:175], v[138:139]
	v_pk_mul_f32 v[136:137], v[136:137], s[8:9] op_sel_hi:[1,0]
	s_nop 0
	v_pk_fma_f32 v[94:95], v[94:95], v[176:177], v[136:137]
	v_add_u32_e32 v136, v140, v156
	ds_read_b64 v[136:137], v136
	s_waitcnt lgkmcnt(0)
	v_cvt_f32_f16_e32 v138, v136
	v_cvt_f32_f16_sdwa v139, v136 dst_sel:DWORD dst_unused:UNUSED_PAD src0_sel:WORD_1
	v_cvt_f32_f16_e32 v136, v137
	v_cvt_f32_f16_sdwa v137, v137 dst_sel:DWORD dst_unused:UNUSED_PAD src0_sel:WORD_1
	v_pk_mul_f32 v[138:139], v[138:139], s[8:9] op_sel_hi:[1,0]
	s_nop 0
	v_pk_fma_f32 v[88:89], v[88:89], v[170:171], v[138:139]
	v_pk_mul_f32 v[136:137], v[136:137], s[8:9] op_sel_hi:[1,0]
	s_nop 0
	v_pk_fma_f32 v[90:91], v[90:91], v[172:173], v[136:137]
	v_add_u32_e32 v136, v140, v180
	ds_read_b64 v[136:137], v136
	s_waitcnt lgkmcnt(0)
	v_cvt_f32_f16_e32 v138, v136
	v_cvt_f32_f16_sdwa v139, v136 dst_sel:DWORD dst_unused:UNUSED_PAD src0_sel:WORD_1
	v_cvt_f32_f16_e32 v136, v137
	v_cvt_f32_f16_sdwa v137, v137 dst_sel:DWORD dst_unused:UNUSED_PAD src0_sel:WORD_1
	v_pk_mul_f32 v[138:139], v[138:139], s[8:9] op_sel_hi:[1,0]
	s_nop 0
	v_pk_fma_f32 v[84:85], v[84:85], v[166:167], v[138:139]
	v_pk_mul_f32 v[136:137], v[136:137], s[8:9] op_sel_hi:[1,0]
	s_nop 0
	v_pk_fma_f32 v[86:87], v[86:87], v[168:169], v[136:137]
	v_add_u32_e32 v136, v140, v152
	ds_read_b64 v[136:137], v136
	s_waitcnt lgkmcnt(0)
	v_cvt_f32_f16_e32 v138, v136
	v_cvt_f32_f16_sdwa v139, v136 dst_sel:DWORD dst_unused:UNUSED_PAD src0_sel:WORD_1
	v_cvt_f32_f16_e32 v136, v137
	v_cvt_f32_f16_sdwa v137, v137 dst_sel:DWORD dst_unused:UNUSED_PAD src0_sel:WORD_1
	v_pk_mul_f32 v[138:139], v[138:139], s[8:9] op_sel_hi:[1,0]
	s_nop 0
	v_pk_fma_f32 v[80:81], v[80:81], v[162:163], v[138:139]
	v_pk_mul_f32 v[136:137], v[136:137], s[8:9] op_sel_hi:[1,0]
	s_nop 0
	v_pk_fma_f32 v[82:83], v[82:83], v[164:165], v[136:137]
	v_add_u32_e32 v136, 0x12000, v184
	v_and_b32_e32 v136, 0xffffbc00, v136
	v_add_u32_e32 v140, v183, v136
	v_add_u32_e32 v136, v140, v182
	ds_read_b64 v[136:137], v136
	s_waitcnt lgkmcnt(0)
	v_cvt_f32_f16_e32 v138, v136
	v_cvt_f32_f16_sdwa v139, v136 dst_sel:DWORD dst_unused:UNUSED_PAD src0_sel:WORD_1
	v_cvt_f32_f16_e32 v136, v137
	v_cvt_f32_f16_sdwa v137, v137 dst_sel:DWORD dst_unused:UNUSED_PAD src0_sel:WORD_1
	v_pk_mul_f32 v[138:139], v[138:139], s[8:9] op_sel_hi:[1,0]
	s_nop 0
	v_pk_fma_f32 v[76:77], v[76:77], v[174:175], v[138:139]
	v_pk_mul_f32 v[136:137], v[136:137], s[8:9] op_sel_hi:[1,0]
	s_nop 0
	v_pk_fma_f32 v[78:79], v[78:79], v[176:177], v[136:137]
	v_add_u32_e32 v136, v140, v156
	ds_read_b64 v[136:137], v136
	s_waitcnt lgkmcnt(0)
	v_cvt_f32_f16_e32 v138, v136
	v_cvt_f32_f16_sdwa v139, v136 dst_sel:DWORD dst_unused:UNUSED_PAD src0_sel:WORD_1
	v_cvt_f32_f16_e32 v136, v137
	v_cvt_f32_f16_sdwa v137, v137 dst_sel:DWORD dst_unused:UNUSED_PAD src0_sel:WORD_1
	v_pk_mul_f32 v[138:139], v[138:139], s[8:9] op_sel_hi:[1,0]
	s_nop 0
	v_pk_fma_f32 v[72:73], v[72:73], v[170:171], v[138:139]
	v_pk_mul_f32 v[136:137], v[136:137], s[8:9] op_sel_hi:[1,0]
	s_nop 0
	v_pk_fma_f32 v[74:75], v[74:75], v[172:173], v[136:137]
	v_add_u32_e32 v136, v140, v180
	ds_read_b64 v[136:137], v136
	s_waitcnt lgkmcnt(0)
	v_cvt_f32_f16_e32 v138, v136
	v_cvt_f32_f16_sdwa v139, v136 dst_sel:DWORD dst_unused:UNUSED_PAD src0_sel:WORD_1
	v_cvt_f32_f16_e32 v136, v137
	v_cvt_f32_f16_sdwa v137, v137 dst_sel:DWORD dst_unused:UNUSED_PAD src0_sel:WORD_1
	v_pk_mul_f32 v[138:139], v[138:139], s[8:9] op_sel_hi:[1,0]
	s_nop 0
	v_pk_fma_f32 v[68:69], v[68:69], v[166:167], v[138:139]
	v_pk_mul_f32 v[136:137], v[136:137], s[8:9] op_sel_hi:[1,0]
	s_nop 0
	v_pk_fma_f32 v[70:71], v[70:71], v[168:169], v[136:137]
	v_add_u32_e32 v136, v140, v152
	ds_read_b64 v[136:137], v136
	v_add_u32_e32 v140, 0x14000, v181
	s_waitcnt lgkmcnt(0)
	v_cvt_f32_f16_e32 v138, v136
	v_cvt_f32_f16_sdwa v139, v136 dst_sel:DWORD dst_unused:UNUSED_PAD src0_sel:WORD_1
	v_cvt_f32_f16_e32 v136, v137
	v_cvt_f32_f16_sdwa v137, v137 dst_sel:DWORD dst_unused:UNUSED_PAD src0_sel:WORD_1
	v_pk_mul_f32 v[138:139], v[138:139], s[8:9] op_sel_hi:[1,0]
	s_nop 0
	v_pk_fma_f32 v[64:65], v[64:65], v[162:163], v[138:139]
	v_pk_mul_f32 v[136:137], v[136:137], s[8:9] op_sel_hi:[1,0]
	s_nop 0
	v_pk_fma_f32 v[66:67], v[66:67], v[164:165], v[136:137]
	v_add_u32_e32 v136, v140, v182
	ds_read_b64 v[136:137], v136
	s_waitcnt lgkmcnt(0)
	v_cvt_f32_f16_e32 v138, v136
	v_cvt_f32_f16_sdwa v139, v136 dst_sel:DWORD dst_unused:UNUSED_PAD src0_sel:WORD_1
	v_cvt_f32_f16_e32 v136, v137
	v_cvt_f32_f16_sdwa v137, v137 dst_sel:DWORD dst_unused:UNUSED_PAD src0_sel:WORD_1
	v_pk_mul_f32 v[138:139], v[138:139], s[8:9] op_sel_hi:[1,0]
	s_nop 0
	v_pk_fma_f32 v[60:61], v[60:61], v[174:175], v[138:139]
	v_pk_mul_f32 v[136:137], v[136:137], s[8:9] op_sel_hi:[1,0]
	s_nop 0
	v_pk_fma_f32 v[62:63], v[62:63], v[176:177], v[136:137]
	v_add_u32_e32 v136, v140, v156
	ds_read_b64 v[136:137], v136
	s_waitcnt lgkmcnt(0)
	v_cvt_f32_f16_e32 v138, v136
	v_cvt_f32_f16_sdwa v139, v136 dst_sel:DWORD dst_unused:UNUSED_PAD src0_sel:WORD_1
	v_cvt_f32_f16_e32 v136, v137
	v_cvt_f32_f16_sdwa v137, v137 dst_sel:DWORD dst_unused:UNUSED_PAD src0_sel:WORD_1
	v_pk_mul_f32 v[138:139], v[138:139], s[8:9] op_sel_hi:[1,0]
	s_nop 0
	v_pk_fma_f32 v[56:57], v[56:57], v[170:171], v[138:139]
	v_pk_mul_f32 v[136:137], v[136:137], s[8:9] op_sel_hi:[1,0]
	s_nop 0
	v_pk_fma_f32 v[58:59], v[58:59], v[172:173], v[136:137]
	v_add_u32_e32 v136, v140, v180
	ds_read_b64 v[136:137], v136
	s_waitcnt lgkmcnt(0)
	v_cvt_f32_f16_e32 v138, v136
	v_cvt_f32_f16_sdwa v139, v136 dst_sel:DWORD dst_unused:UNUSED_PAD src0_sel:WORD_1
	v_cvt_f32_f16_e32 v136, v137
	v_cvt_f32_f16_sdwa v137, v137 dst_sel:DWORD dst_unused:UNUSED_PAD src0_sel:WORD_1
	v_pk_mul_f32 v[138:139], v[138:139], s[8:9] op_sel_hi:[1,0]
	s_nop 0
	v_pk_fma_f32 v[52:53], v[52:53], v[166:167], v[138:139]
	v_pk_mul_f32 v[136:137], v[136:137], s[8:9] op_sel_hi:[1,0]
	s_nop 0
	v_pk_fma_f32 v[54:55], v[54:55], v[168:169], v[136:137]
	v_add_u32_e32 v136, v140, v152
	ds_read_b64 v[136:137], v136
	v_add_u32_e32 v140, 0x16000, v181
	s_waitcnt lgkmcnt(0)
	v_cvt_f32_f16_e32 v138, v136
	v_cvt_f32_f16_sdwa v139, v136 dst_sel:DWORD dst_unused:UNUSED_PAD src0_sel:WORD_1
	v_cvt_f32_f16_e32 v136, v137
	v_cvt_f32_f16_sdwa v137, v137 dst_sel:DWORD dst_unused:UNUSED_PAD src0_sel:WORD_1
	v_pk_mul_f32 v[138:139], v[138:139], s[8:9] op_sel_hi:[1,0]
	s_nop 0
	v_pk_fma_f32 v[48:49], v[48:49], v[162:163], v[138:139]
	v_pk_mul_f32 v[136:137], v[136:137], s[8:9] op_sel_hi:[1,0]
	s_nop 0
	v_pk_fma_f32 v[50:51], v[50:51], v[164:165], v[136:137]
	v_add_u32_e32 v136, v140, v182
	ds_read_b64 v[136:137], v136
	s_waitcnt lgkmcnt(0)
	v_cvt_f32_f16_e32 v138, v136
	v_cvt_f32_f16_sdwa v139, v136 dst_sel:DWORD dst_unused:UNUSED_PAD src0_sel:WORD_1
	v_cvt_f32_f16_e32 v136, v137
	v_cvt_f32_f16_sdwa v137, v137 dst_sel:DWORD dst_unused:UNUSED_PAD src0_sel:WORD_1
	v_pk_mul_f32 v[138:139], v[138:139], s[8:9] op_sel_hi:[1,0]
	s_nop 0
	v_pk_fma_f32 v[44:45], v[44:45], v[174:175], v[138:139]
	v_pk_mul_f32 v[136:137], v[136:137], s[8:9] op_sel_hi:[1,0]
	s_nop 0
	v_pk_fma_f32 v[46:47], v[46:47], v[176:177], v[136:137]
	v_add_u32_e32 v136, v140, v156
	ds_read_b64 v[136:137], v136
	v_xor_b32_e32 v156, 0x80, v24
	s_waitcnt lgkmcnt(0)
	v_cvt_f32_f16_e32 v138, v136
	v_cvt_f32_f16_sdwa v139, v136 dst_sel:DWORD dst_unused:UNUSED_PAD src0_sel:WORD_1
	v_cvt_f32_f16_e32 v136, v137
	v_cvt_f32_f16_sdwa v137, v137 dst_sel:DWORD dst_unused:UNUSED_PAD src0_sel:WORD_1
	v_pk_mul_f32 v[138:139], v[138:139], s[8:9] op_sel_hi:[1,0]
	s_nop 0
	v_pk_fma_f32 v[40:41], v[40:41], v[170:171], v[138:139]
	v_pk_mul_f32 v[136:137], v[136:137], s[8:9] op_sel_hi:[1,0]
	s_nop 0
	v_pk_fma_f32 v[42:43], v[42:43], v[172:173], v[136:137]
	v_add_u32_e32 v136, v140, v180
	ds_read_b64 v[136:137], v136
	s_waitcnt lgkmcnt(0)
	v_cvt_f32_f16_e32 v138, v136
	v_cvt_f32_f16_sdwa v139, v136 dst_sel:DWORD dst_unused:UNUSED_PAD src0_sel:WORD_1
	v_cvt_f32_f16_e32 v136, v137
	v_cvt_f32_f16_sdwa v137, v137 dst_sel:DWORD dst_unused:UNUSED_PAD src0_sel:WORD_1
	v_pk_mul_f32 v[138:139], v[138:139], s[8:9] op_sel_hi:[1,0]
	s_nop 0
	v_pk_fma_f32 v[36:37], v[36:37], v[166:167], v[138:139]
	v_pk_mul_f32 v[136:137], v[136:137], s[8:9] op_sel_hi:[1,0]
	s_nop 0
	v_pk_fma_f32 v[38:39], v[38:39], v[168:169], v[136:137]
	v_add_u32_e32 v136, v140, v152
	ds_read_b64 v[136:137], v136
	v_pk_add_f32 v[152:153], v[6:7], v[18:19]
	v_pk_add_f32 v[140:141], v[2:3], v[26:27]
	v_pk_mov_b32 v[24:25], v[154:155], v[152:153] op_sel:[1,0]
	v_mov_b32_e32 v26, v154
	s_waitcnt lgkmcnt(0)
	v_cvt_f32_f16_e32 v138, v136
	v_cvt_f32_f16_sdwa v139, v136 dst_sel:DWORD dst_unused:UNUSED_PAD src0_sel:WORD_1
	v_cvt_f32_f16_e32 v136, v137
	v_cvt_f32_f16_sdwa v137, v137 dst_sel:DWORD dst_unused:UNUSED_PAD src0_sel:WORD_1
	v_mov_b32_e32 v27, v153
	v_pk_add_f32 v[18:19], v[8:9], v[144:145]
	v_pk_add_f32 v[24:25], v[24:25], v[26:27]
	v_pk_mov_b32 v[26:27], v[142:143], v[140:141] op_sel:[1,0]
	v_mov_b32_e32 v144, v142
	v_mov_b32_e32 v145, v141
	v_pk_mul_f32 v[138:139], v[138:139], s[8:9] op_sel_hi:[1,0]
	v_pk_mul_f32 v[136:137], v[136:137], s[8:9] op_sel_hi:[1,0]
	v_pk_add_f32 v[26:27], v[26:27], v[144:145]
	v_pk_fma_f32 v[34:35], v[34:35], v[164:165], v[136:137]
	v_pk_fma_f32 v[32:33], v[32:33], v[162:163], v[138:139]
	v_pk_add_f32 v[136:137], v[14:15], v[150:151]
	v_pk_add_f32 v[138:139], v[12:13], v[148:149]
	v_add_f32_e32 v24, v24, v25
	v_pk_add_f32 v[26:27], v[26:27], v[26:27] op_sel_hi:[0,1]
	v_add_f32_e32 v25, 0, v24
	v_add_f32_e32 v145, v138, v139
	v_add_f32_e32 v147, v136, v137
	v_mov_b32_e32 v144, v18
	v_mov_b32_e32 v146, v19
	v_mov_b32_e32 v26, v16
	v_mov_b32_e32 v24, v17
	v_pk_add_f32 v[144:145], v[144:145], v[146:147]
	v_pk_add_f32 v[24:25], v[26:27], v[24:25]
	s_waitcnt lgkmcnt(0)
	s_barrier
	v_pk_add_f32 v[24:25], v[144:145], v[24:25]
	s_nop 0
	v_add_f32_e32 v24, v24, v25
	s_mov_b32 s100, 0xffff0000
	s_mov_b32 s101, 0xffff0000
	s_mov_b32 s98, 0
	s_mov_b32 s99, -1
	v_mov_b32_e32 v25, v24
	v_mov_b32_e32 v210, v24
	s_nop 1
	v_permlane16_swap_b32_e32 v25, v210
	v_cndmask_b32_e64 v25, v210, v25, s[100:101]
	s_waitcnt lgkmcnt(0)
	v_add_f32_e32 v24, v24, v25
	v_mov_b32_e32 v25, v24
	v_mov_b32_e32 v210, v24
	s_nop 1
	v_permlane32_swap_b32_e32 v25, v210
	v_cndmask_b32_e64 v25, v210, v25, s[98:99]
	s_waitcnt lgkmcnt(0)
	v_add_f32_e32 v24, v24, v25
	v_fmamk_f32 v26, v24, 0xbc800000, v153
	v_fmamk_f32 v144, v24, 0xbc800000, v155
	v_fmamk_f32 v25, v24, 0xbc800000, v152
	v_fmamk_f32 v27, v24, 0xbc800000, v154
	v_mul_f32_e32 v144, v144, v144
	v_mul_f32_e32 v26, v26, v26
	v_fmac_f32_e32 v144, v27, v27
	v_fmac_f32_e32 v26, v25, v25
	v_fmamk_f32 v27, v24, 0xbc800000, v141
	v_fmamk_f32 v145, v24, 0xbc800000, v143
	v_add_f32_e32 v25, v144, v26
	v_fmamk_f32 v26, v24, 0xbc800000, v140
	v_fmamk_f32 v144, v24, 0xbc800000, v142
	v_mul_f32_e32 v145, v145, v145
	v_mul_f32_e32 v27, v27, v27
	v_fmac_f32_e32 v145, v144, v144
	v_fmac_f32_e32 v27, v26, v26
	v_add_f32_e32 v26, v145, v27
	v_fmamk_f32 v27, v24, 0xbc800000, v137
	v_fmamk_f32 v145, v24, 0xbc800000, v139
	v_add_f32_e32 v25, v25, v26
	v_fmamk_f32 v26, v24, 0xbc800000, v136
	v_fmamk_f32 v144, v24, 0xbc800000, v138
	v_mul_f32_e32 v145, v145, v145
	v_mul_f32_e32 v27, v27, v27
	v_fmac_f32_e32 v145, v144, v144
	v_fmac_f32_e32 v27, v26, v26
	v_add_f32_e32 v26, v145, v27
	v_fmamk_f32 v27, v24, 0xbc800000, v17
	v_fmamk_f32 v145, v24, 0xbc800000, v19
	v_add_f32_e32 v25, v26, v25
	v_fmamk_f32 v26, v24, 0xbc800000, v16
	v_fmamk_f32 v144, v24, 0xbc800000, v18
	v_mul_f32_e32 v145, v145, v145
	v_mul_f32_e32 v27, v27, v27
	v_fmac_f32_e32 v145, v144, v144
	v_fmac_f32_e32 v27, v26, v26
	v_add_f32_e32 v26, v145, v27
	v_add_f32_e32 v25, v26, v25
	v_mov_b32_e32 v26, v25
	v_mov_b32_e32 v210, v25
	s_nop 1
	v_permlane16_swap_b32_e32 v26, v210
	v_cndmask_b32_e64 v26, v210, v26, s[100:101]
	s_waitcnt lgkmcnt(0)
	v_add_f32_e32 v25, v25, v26
	v_mov_b32_e32 v26, v25
	v_mov_b32_e32 v210, v25
	s_nop 1
	v_permlane32_swap_b32_e32 v26, v210
	v_cndmask_b32_e64 v26, v210, v26, s[98:99]
	s_and_saveexec_b64 s[8:9], vcc
	s_cbranch_execz .LBB0_417
	s_lshl_b32 s3, s22, 11
	s_add_i32 s3, s12, s3
	v_mul_f32_e32 v24, 0x3c800000, v24
	s_waitcnt lgkmcnt(0)
	v_add_f32_e32 v25, v25, v26
	v_lshl_add_u32 v26, v178, 5, s3
	ds_write_b64 v26, v[24:25]

.LBB0_851:
	v_lshl_add_u64 v[20:21], v[160:161], 2, s[18:19]
	global_load_dwordx4 v[196:199], v[20:21], off
	global_load_dwordx4 v[200:203], v[20:21], off offset:64
	global_load_dwordx4 v[204:207], v[20:21], off offset:512
	global_load_dwordx4 v[208:211], v[20:21], off offset:576
	s_mov_b32 s8, 0x3a800000
	s_lshl_b32 s10, s26, 5
	v_readlane_b32 s3, v254, 17
	s_add_i32 s3, s3, s10
	v_cmp_gt_u32_e32 vcc, 16, v178
	v_mbcnt_lo_u32_b32 v185, -1, 0
	v_mbcnt_hi_u32_b32 v185, -1, v185
	v_ashrrev_i32_e32 v30, 5, v185
	v_add_u32_e32 v16, s3, v30
	v_and_b32_e32 v31, 31, v185
	v_ashrrev_i32_e32 v17, 31, v16
	v_readlane_b32 s8, v253, 47
	v_lshlrev_b64 v[16:17], 11, v[16:17]
	v_readlane_b32 s9, v253, 48
	s_lshl_b32 s3, s26, 14
	v_bitop3_b32 v18, v30, v31, 15 bitop3:0x6c
	v_lshl_add_u64 v[16:17], s[8:9], 0, v[16:17]
	s_add_i32 s3, s3, 0
	v_lshlrev_b32_e32 v230, 4, v18
	v_lshl_add_u64 v[18:19], v[16:17], 0, v[230:231]
	s_mov_b32 m0, s3
	s_mov_b64 s[8:9], 0x1000
	global_load_lds_dwordx4 v[18:19], off
	v_lshl_add_u64 v[18:19], v[16:17], 0, s[8:9]
	v_add_u32_e32 v16, 2, v30
	v_bitop3_b32 v16, v16, v31, 15 bitop3:0x6c
	v_lshlrev_b32_e32 v16, 4, v16
	v_mov_b32_e32 v17, v231
	s_add_i32 m0, s3, 0x400
	v_lshl_add_u64 v[20:21], v[18:19], 0, v[16:17]
	global_load_lds_dwordx4 v[20:21], off
	v_lshl_add_u64 v[20:21], v[18:19], 0, s[8:9]
	v_add_u32_e32 v18, 4, v30
	v_bitop3_b32 v18, v18, v31, 15 bitop3:0x6c
	v_lshlrev_b32_e32 v18, 4, v18
	v_mov_b32_e32 v19, v231
	s_add_i32 m0, s3, 0x800
	v_lshl_add_u64 v[22:23], v[20:21], 0, v[18:19]
	global_load_lds_dwordx4 v[22:23], off
	v_lshl_add_u64 v[22:23], v[20:21], 0, s[8:9]
	v_add_u32_e32 v20, 6, v30
	v_bitop3_b32 v20, v20, v31, 15 bitop3:0x6c
	v_lshlrev_b32_e32 v20, 4, v20
	v_mov_b32_e32 v21, v231
	s_add_i32 m0, s3, 0xc00
	v_lshl_add_u64 v[24:25], v[22:23], 0, v[20:21]
	global_load_lds_dwordx4 v[24:25], off
	v_lshl_add_u64 v[24:25], v[22:23], 0, s[8:9]
	v_xor_b32_e32 v22, 0x80, v230
	v_mov_b32_e32 v23, v231
	s_add_i32 m0, s3, 0x1000
	v_lshl_add_u64 v[26:27], v[24:25], 0, v[22:23]
	global_load_lds_dwordx4 v[26:27], off
	v_lshl_add_u64 v[26:27], v[24:25], 0, s[8:9]
	v_add_u32_e32 v24, 10, v30
	v_bitop3_b32 v24, v24, v31, 15 bitop3:0x6c
	v_lshlrev_b32_e32 v24, 4, v24
	v_mov_b32_e32 v25, v231
	s_add_i32 m0, s3, 0x1400
	v_lshl_add_u64 v[28:29], v[26:27], 0, v[24:25]
	global_load_lds_dwordx4 v[28:29], off
	v_add_u32_e32 v28, 12, v30
	v_bitop3_b32 v28, v28, v31, 15 bitop3:0x6c
	v_lshl_add_u64 v[26:27], v[26:27], 0, s[8:9]
	v_lshlrev_b32_e32 v28, 4, v28
	v_mov_b32_e32 v29, v231
	s_add_i32 m0, s3, 0x1800
	v_lshl_add_u64 v[180:181], v[26:27], 0, v[28:29]
	global_load_lds_dwordx4 v[180:181], off
	v_add_u32_e32 v180, 14, v30
	v_lshl_add_u64 v[26:27], v[26:27], 0, s[8:9]
	v_bitop3_b32 v31, v180, v31, 15 bitop3:0x6c
	v_lshlrev_b32_e32 v180, 4, v31
	v_mov_b32_e32 v181, v231
	v_lshl_add_u64 v[182:183], v[26:27], 0, v[180:181]
	s_add_i32 m0, s3, 0x1c00
	v_lshl_add_u64 v[26:27], v[26:27], 0, s[8:9]
	global_load_lds_dwordx4 v[182:183], off
	s_add_i32 m0, s3, 0x2000
	v_lshl_add_u64 v[182:183], v[26:27], 0, v[230:231]
	v_lshl_add_u64 v[26:27], v[26:27], 0, s[8:9]
	global_load_lds_dwordx4 v[182:183], off
	s_add_i32 m0, s3, 0x2400
	v_lshl_add_u64 v[16:17], v[26:27], 0, v[16:17]
	global_load_lds_dwordx4 v[16:17], off
	v_lshl_add_u64 v[16:17], v[26:27], 0, s[8:9]
	s_add_i32 m0, s3, 0x2800
	v_lshl_add_u64 v[18:19], v[16:17], 0, v[18:19]
	v_lshl_add_u64 v[16:17], v[16:17], 0, s[8:9]
	global_load_lds_dwordx4 v[18:19], off
	s_add_i32 m0, s3, 0x2c00
	v_lshl_add_u64 v[18:19], v[16:17], 0, v[20:21]
	v_lshl_add_u64 v[16:17], v[16:17], 0, s[8:9]
	global_load_lds_dwordx4 v[18:19], off
	s_add_i32 m0, s3, 0x3000
	v_lshl_add_u64 v[18:19], v[16:17], 0, v[22:23]
	v_lshl_add_u64 v[16:17], v[16:17], 0, s[8:9]
	global_load_lds_dwordx4 v[18:19], off
	s_add_i32 m0, s3, 0x3400
	v_lshl_add_u64 v[18:19], v[16:17], 0, v[24:25]
	v_lshl_add_u64 v[16:17], v[16:17], 0, s[8:9]
	global_load_lds_dwordx4 v[18:19], off
	s_add_i32 m0, s3, 0x3800
	v_lshl_add_u64 v[18:19], v[16:17], 0, v[28:29]
	v_lshl_add_u64 v[16:17], v[16:17], 0, s[8:9]
	global_load_lds_dwordx4 v[18:19], off
	s_add_i32 m0, s3, 0x3c00
	v_lshl_add_u64 v[18:19], v[16:17], 0, v[180:181]
	v_lshl_add_u64 v[16:17], v[16:17], 0, s[8:9]
	global_load_lds_dwordx4 v[18:19], off
	v_lshrrev_b32_e32 v18, 1, v185
	v_lshlrev_b32_e32 v17, 9, v185
	v_and_b32_e32 v17, 0x200, v17
	v_and_b32_e32 v18, 8, v18
	v_lshl_add_u32 v187, s25, 2, v30
	v_and_b32_e32 v16, 15, v185
	v_add3_u32 v183, 0, v17, v18
	v_add_u32_e32 v17, 16, v187
	v_bitop3_b32 v17, v17, v185, 15 bitop3:0x78
	s_lshl_b32 s3, s24, 15
	v_lshlrev_b32_e32 v16, 9, v16
	v_lshlrev_b32_e32 v180, 4, v17
	v_or_b32_e32 v184, s3, v16
	v_mov_b32_e32 v17, s3
	s_movk_i32 s3, 0x9c00
	v_bitop3_b32 v16, v16, s3, v17 bitop3:0xc8
	v_add_u32_e32 v181, v183, v16
	v_bitop3_b32 v16, v187, v185, 15 bitop3:0x78
	v_lshlrev_b32_e32 v182, 4, v16
	s_waitcnt vmcnt(0)
	s_mov_b32 s100, 0x3a800000
	v_pk_mul_f32 v[174:175], v[198:199], s[100:101] op_sel_hi:[1,0]
	v_pk_mul_f32 v[176:177], v[196:197], s[100:101] op_sel_hi:[1,0]
	v_pk_mul_f32 v[170:171], v[202:203], s[100:101] op_sel_hi:[1,0]
	v_pk_mul_f32 v[172:173], v[200:201], s[100:101] op_sel_hi:[1,0]
	v_pk_mul_f32 v[166:167], v[206:207], s[100:101] op_sel_hi:[1,0]
	v_pk_mul_f32 v[168:169], v[204:205], s[100:101] op_sel_hi:[1,0]
	v_pk_mul_f32 v[164:165], v[208:209], s[100:101] op_sel_hi:[1,0]
	v_pk_mul_f32 v[162:163], v[210:211], s[100:101] op_sel_hi:[1,0]
	s_barrier
	v_add_u32_e32 v186, v181, v182
	ds_read_b64 v[16:17], v186
	s_mov_b32 s8, 0x3fd744fd
	s_lshl_b32 s3, s25, 3
	s_add_i32 s11, s3, 0
	s_waitcnt lgkmcnt(0)
	v_cvt_f32_f16_e32 v18, v16
	v_cvt_f32_f16_sdwa v19, v16 dst_sel:DWORD dst_unused:UNUSED_PAD src0_sel:WORD_1
	v_cvt_f32_f16_e32 v16, v17
	v_cvt_f32_f16_sdwa v17, v17 dst_sel:DWORD dst_unused:UNUSED_PAD src0_sel:WORD_1
	v_pk_mul_f32 v[20:21], v[18:19], s[8:9] op_sel_hi:[1,0]
	v_pk_mul_f32 v[16:17], v[16:17], s[8:9] op_sel_hi:[1,0]
	s_nop 0
	v_pk_fma_f32 v[18:19], v[158:159], v[174:175], v[16:17]
	v_pk_fma_f32 v[16:17], v[156:157], v[176:177], v[20:21]
	v_add_u32_e32 v20, 2, v187
	v_bitop3_b32 v20, v20, v185, 15 bitop3:0x78
	v_lshlrev_b32_e32 v156, 4, v20
	v_add_u32_e32 v157, v181, v156
	ds_read_b64 v[20:21], v157
	s_waitcnt lgkmcnt(0)
	v_cvt_f32_f16_e32 v22, v20
	v_cvt_f32_f16_sdwa v23, v20 dst_sel:DWORD dst_unused:UNUSED_PAD src0_sel:WORD_1
	v_cvt_f32_f16_e32 v20, v21
	v_cvt_f32_f16_sdwa v21, v21 dst_sel:DWORD dst_unused:UNUSED_PAD src0_sel:WORD_1
	v_pk_mul_f32 v[24:25], v[22:23], s[8:9] op_sel_hi:[1,0]
	v_pk_mul_f32 v[20:21], v[20:21], s[8:9] op_sel_hi:[1,0]
	s_nop 0
	v_pk_fma_f32 v[22:23], v[154:155], v[170:171], v[20:21]
	v_pk_fma_f32 v[20:21], v[152:153], v[172:173], v[24:25]
	v_add_u32_e32 v152, v181, v180
	ds_read_b64 v[24:25], v152
	s_waitcnt lgkmcnt(0)
	v_cvt_f32_f16_e32 v26, v24
	v_cvt_f32_f16_sdwa v27, v24 dst_sel:DWORD dst_unused:UNUSED_PAD src0_sel:WORD_1
	v_cvt_f32_f16_e32 v24, v25
	v_cvt_f32_f16_sdwa v25, v25 dst_sel:DWORD dst_unused:UNUSED_PAD src0_sel:WORD_1
	v_pk_mul_f32 v[26:27], v[26:27], s[8:9] op_sel_hi:[1,0]
	s_nop 0
	v_pk_fma_f32 v[28:29], v[148:149], v[168:169], v[26:27]
	v_pk_mul_f32 v[24:25], v[24:25], s[8:9] op_sel_hi:[1,0]
	s_nop 0
	v_pk_fma_f32 v[30:31], v[150:151], v[166:167], v[24:25]
	v_add_u32_e32 v24, 18, v187
	v_bitop3_b32 v24, v24, v185, 15 bitop3:0x78
	v_lshlrev_b32_e32 v148, 4, v24
	v_add_u32_e32 v149, v181, v148
	ds_read_b64 v[24:25], v149
	s_waitcnt lgkmcnt(0)
	v_cvt_f32_f16_e32 v26, v24
	v_cvt_f32_f16_sdwa v27, v24 dst_sel:DWORD dst_unused:UNUSED_PAD src0_sel:WORD_1
	v_cvt_f32_f16_e32 v24, v25
	v_cvt_f32_f16_sdwa v25, v25 dst_sel:DWORD dst_unused:UNUSED_PAD src0_sel:WORD_1
	v_pk_mul_f32 v[26:27], v[26:27], s[8:9] op_sel_hi:[1,0]
	s_nop 0
	v_pk_fma_f32 v[144:145], v[144:145], v[164:165], v[26:27]
	v_pk_mul_f32 v[24:25], v[24:25], s[8:9] op_sel_hi:[1,0]
	s_nop 0
	v_pk_fma_f32 v[146:147], v[146:147], v[162:163], v[24:25]
	s_nop 0
	ds_read_b64 v[24:25], v186 offset:8192
	v_pk_add_f32 v[154:155], v[4:5], v[16:17]
	v_pk_add_f32 v[16:17], v[10:11], v[146:147]
	s_waitcnt lgkmcnt(0)
	v_cvt_f32_f16_e32 v26, v24
	v_cvt_f32_f16_sdwa v27, v24 dst_sel:DWORD dst_unused:UNUSED_PAD src0_sel:WORD_1
	v_cvt_f32_f16_e32 v24, v25
	v_cvt_f32_f16_sdwa v25, v25 dst_sel:DWORD dst_unused:UNUSED_PAD src0_sel:WORD_1
	v_pk_mul_f32 v[150:151], v[26:27], s[8:9] op_sel_hi:[1,0]
	v_pk_mul_f32 v[24:25], v[24:25], s[8:9] op_sel_hi:[1,0]
	s_nop 0
	v_pk_fma_f32 v[26:27], v[142:143], v[174:175], v[24:25]
	v_pk_fma_f32 v[24:25], v[140:141], v[176:177], v[150:151]
	ds_read_b64 v[140:141], v157 offset:8192
	v_pk_add_f32 v[150:151], v[0:1], v[20:21]
	v_lshlrev_b32_e32 v20, 2, v178
	s_waitcnt lgkmcnt(0)
	v_cvt_f32_f16_e32 v142, v140
	v_cvt_f32_f16_sdwa v143, v140 dst_sel:DWORD dst_unused:UNUSED_PAD src0_sel:WORD_1
	v_cvt_f32_f16_e32 v140, v141
	v_cvt_f32_f16_sdwa v141, v141 dst_sel:DWORD dst_unused:UNUSED_PAD src0_sel:WORD_1
	v_pk_mul_f32 v[142:143], v[142:143], s[8:9] op_sel_hi:[1,0]
	s_nop 0
	v_pk_fma_f32 v[136:137], v[136:137], v[172:173], v[142:143]
	v_pk_mul_f32 v[140:141], v[140:141], s[8:9] op_sel_hi:[1,0]
	s_nop 0
	v_pk_fma_f32 v[138:139], v[138:139], v[170:171], v[140:141]
	ds_read_b64 v[140:141], v152 offset:8192
	s_waitcnt lgkmcnt(0)
	v_cvt_f32_f16_e32 v142, v140
	v_cvt_f32_f16_sdwa v143, v140 dst_sel:DWORD dst_unused:UNUSED_PAD src0_sel:WORD_1
	v_cvt_f32_f16_e32 v140, v141
	v_cvt_f32_f16_sdwa v141, v141 dst_sel:DWORD dst_unused:UNUSED_PAD src0_sel:WORD_1
	v_pk_mul_f32 v[142:143], v[142:143], s[8:9] op_sel_hi:[1,0]
	s_nop 0
	v_pk_fma_f32 v[132:133], v[132:133], v[168:169], v[142:143]
	v_pk_mul_f32 v[140:141], v[140:141], s[8:9] op_sel_hi:[1,0]
	s_nop 0
	v_pk_fma_f32 v[134:135], v[134:135], v[166:167], v[140:141]
	ds_read_b64 v[140:141], v149 offset:8192
	s_waitcnt lgkmcnt(0)
	v_cvt_f32_f16_e32 v142, v140
	v_cvt_f32_f16_sdwa v143, v140 dst_sel:DWORD dst_unused:UNUSED_PAD src0_sel:WORD_1
	v_cvt_f32_f16_e32 v140, v141
	v_cvt_f32_f16_sdwa v141, v141 dst_sel:DWORD dst_unused:UNUSED_PAD src0_sel:WORD_1
	v_pk_mul_f32 v[142:143], v[142:143], s[8:9] op_sel_hi:[1,0]
	s_nop 0
	v_pk_fma_f32 v[128:129], v[128:129], v[164:165], v[142:143]
	v_pk_mul_f32 v[140:141], v[140:141], s[8:9] op_sel_hi:[1,0]
	s_nop 0
	v_pk_fma_f32 v[130:131], v[130:131], v[162:163], v[140:141]
	s_nop 0
	ds_read_b64 v[140:141], v186 offset:16384
	s_waitcnt lgkmcnt(0)
	v_cvt_f32_f16_e32 v142, v140
	v_cvt_f32_f16_sdwa v143, v140 dst_sel:DWORD dst_unused:UNUSED_PAD src0_sel:WORD_1
	v_cvt_f32_f16_e32 v140, v141
	v_cvt_f32_f16_sdwa v141, v141 dst_sel:DWORD dst_unused:UNUSED_PAD src0_sel:WORD_1
	v_pk_mul_f32 v[142:143], v[142:143], s[8:9] op_sel_hi:[1,0]
	s_nop 0
	v_pk_fma_f32 v[124:125], v[124:125], v[176:177], v[142:143]
	v_pk_mul_f32 v[140:141], v[140:141], s[8:9] op_sel_hi:[1,0]
	s_nop 0
	v_pk_fma_f32 v[126:127], v[126:127], v[174:175], v[140:141]
	ds_read_b64 v[140:141], v157 offset:16384
	s_waitcnt lgkmcnt(0)
	v_cvt_f32_f16_e32 v142, v140
	v_cvt_f32_f16_sdwa v143, v140 dst_sel:DWORD dst_unused:UNUSED_PAD src0_sel:WORD_1
	v_cvt_f32_f16_e32 v140, v141
	v_cvt_f32_f16_sdwa v141, v141 dst_sel:DWORD dst_unused:UNUSED_PAD src0_sel:WORD_1
	v_pk_mul_f32 v[142:143], v[142:143], s[8:9] op_sel_hi:[1,0]
	s_nop 0
	v_pk_fma_f32 v[120:121], v[120:121], v[172:173], v[142:143]
	v_pk_mul_f32 v[140:141], v[140:141], s[8:9] op_sel_hi:[1,0]
	s_nop 0
	v_pk_fma_f32 v[122:123], v[122:123], v[170:171], v[140:141]
	ds_read_b64 v[140:141], v152 offset:16384
	s_waitcnt lgkmcnt(0)
	v_cvt_f32_f16_e32 v142, v140
	v_cvt_f32_f16_sdwa v143, v140 dst_sel:DWORD dst_unused:UNUSED_PAD src0_sel:WORD_1
	v_cvt_f32_f16_e32 v140, v141
	v_cvt_f32_f16_sdwa v141, v141 dst_sel:DWORD dst_unused:UNUSED_PAD src0_sel:WORD_1
	v_pk_mul_f32 v[142:143], v[142:143], s[8:9] op_sel_hi:[1,0]
	s_nop 0
	v_pk_fma_f32 v[116:117], v[116:117], v[168:169], v[142:143]
	v_pk_mul_f32 v[140:141], v[140:141], s[8:9] op_sel_hi:[1,0]
	s_nop 0
	v_pk_fma_f32 v[118:119], v[118:119], v[166:167], v[140:141]
	ds_read_b64 v[140:141], v149 offset:16384
	s_waitcnt lgkmcnt(0)
	v_cvt_f32_f16_e32 v142, v140
	v_cvt_f32_f16_sdwa v143, v140 dst_sel:DWORD dst_unused:UNUSED_PAD src0_sel:WORD_1
	v_cvt_f32_f16_e32 v140, v141
	v_cvt_f32_f16_sdwa v141, v141 dst_sel:DWORD dst_unused:UNUSED_PAD src0_sel:WORD_1
	v_pk_mul_f32 v[142:143], v[142:143], s[8:9] op_sel_hi:[1,0]
	s_nop 0
	v_pk_fma_f32 v[112:113], v[112:113], v[164:165], v[142:143]
	v_pk_mul_f32 v[140:141], v[140:141], s[8:9] op_sel_hi:[1,0]
	s_nop 0
	v_pk_fma_f32 v[114:115], v[114:115], v[162:163], v[140:141]
	s_nop 0
	ds_read_b64 v[140:141], v186 offset:24576
	s_waitcnt lgkmcnt(0)
	v_cvt_f32_f16_e32 v142, v140
	v_cvt_f32_f16_sdwa v143, v140 dst_sel:DWORD dst_unused:UNUSED_PAD src0_sel:WORD_1
	v_cvt_f32_f16_e32 v140, v141
	v_cvt_f32_f16_sdwa v141, v141 dst_sel:DWORD dst_unused:UNUSED_PAD src0_sel:WORD_1
	v_pk_mul_f32 v[142:143], v[142:143], s[8:9] op_sel_hi:[1,0]
	s_nop 0
	v_pk_fma_f32 v[108:109], v[108:109], v[176:177], v[142:143]
	v_pk_mul_f32 v[140:141], v[140:141], s[8:9] op_sel_hi:[1,0]
	s_nop 0
	v_pk_fma_f32 v[110:111], v[110:111], v[174:175], v[140:141]
	ds_read_b64 v[140:141], v157 offset:24576
	s_waitcnt lgkmcnt(0)
	v_cvt_f32_f16_e32 v142, v140
	v_cvt_f32_f16_sdwa v143, v140 dst_sel:DWORD dst_unused:UNUSED_PAD src0_sel:WORD_1
	v_cvt_f32_f16_e32 v140, v141
	v_cvt_f32_f16_sdwa v141, v141 dst_sel:DWORD dst_unused:UNUSED_PAD src0_sel:WORD_1
	v_pk_mul_f32 v[142:143], v[142:143], s[8:9] op_sel_hi:[1,0]
	s_nop 0
	v_pk_fma_f32 v[104:105], v[104:105], v[172:173], v[142:143]
	v_pk_mul_f32 v[140:141], v[140:141], s[8:9] op_sel_hi:[1,0]
	s_nop 0
	v_pk_fma_f32 v[106:107], v[106:107], v[170:171], v[140:141]
	ds_read_b64 v[140:141], v152 offset:24576
	v_pk_add_f32 v[152:153], v[6:7], v[18:19]
	v_pk_add_f32 v[18:19], v[8:9], v[144:145]
	s_waitcnt lgkmcnt(0)
	v_cvt_f32_f16_e32 v142, v140
	v_cvt_f32_f16_sdwa v143, v140 dst_sel:DWORD dst_unused:UNUSED_PAD src0_sel:WORD_1
	v_cvt_f32_f16_e32 v140, v141
	v_cvt_f32_f16_sdwa v141, v141 dst_sel:DWORD dst_unused:UNUSED_PAD src0_sel:WORD_1
	v_pk_mul_f32 v[142:143], v[142:143], s[8:9] op_sel_hi:[1,0]
	s_nop 0
	v_pk_fma_f32 v[100:101], v[100:101], v[168:169], v[142:143]
	v_pk_mul_f32 v[140:141], v[140:141], s[8:9] op_sel_hi:[1,0]
	s_nop 0
	v_pk_fma_f32 v[102:103], v[102:103], v[166:167], v[140:141]
	ds_read_b64 v[140:141], v149 offset:24576
	v_add_u32_e32 v149, 0x10000, v181
	s_waitcnt lgkmcnt(0)
	v_cvt_f32_f16_e32 v142, v140
	v_cvt_f32_f16_sdwa v143, v140 dst_sel:DWORD dst_unused:UNUSED_PAD src0_sel:WORD_1
	v_cvt_f32_f16_e32 v140, v141
	v_cvt_f32_f16_sdwa v141, v141 dst_sel:DWORD dst_unused:UNUSED_PAD src0_sel:WORD_1
	v_pk_mul_f32 v[142:143], v[142:143], s[8:9] op_sel_hi:[1,0]
	s_nop 0
	v_pk_fma_f32 v[96:97], v[96:97], v[164:165], v[142:143]
	v_pk_mul_f32 v[140:141], v[140:141], s[8:9] op_sel_hi:[1,0]
	s_nop 0
	v_pk_fma_f32 v[98:99], v[98:99], v[162:163], v[140:141]
	v_add_u32_e32 v140, v149, v182
	ds_read_b64 v[140:141], v140
	s_waitcnt lgkmcnt(0)
	v_cvt_f32_f16_e32 v142, v140
	v_cvt_f32_f16_sdwa v143, v140 dst_sel:DWORD dst_unused:UNUSED_PAD src0_sel:WORD_1
	v_cvt_f32_f16_e32 v140, v141
	v_cvt_f32_f16_sdwa v141, v141 dst_sel:DWORD dst_unused:UNUSED_PAD src0_sel:WORD_1
	v_pk_mul_f32 v[142:143], v[142:143], s[8:9] op_sel_hi:[1,0]
	s_nop 0
	v_pk_fma_f32 v[92:93], v[92:93], v[176:177], v[142:143]
	v_pk_mul_f32 v[140:141], v[140:141], s[8:9] op_sel_hi:[1,0]
	s_nop 0
	v_pk_fma_f32 v[94:95], v[94:95], v[174:175], v[140:141]
	v_add_u32_e32 v140, v149, v156
	ds_read_b64 v[140:141], v140
	s_waitcnt lgkmcnt(0)
	v_cvt_f32_f16_e32 v142, v140
	v_cvt_f32_f16_sdwa v143, v140 dst_sel:DWORD dst_unused:UNUSED_PAD src0_sel:WORD_1
	v_cvt_f32_f16_e32 v140, v141
	v_cvt_f32_f16_sdwa v141, v141 dst_sel:DWORD dst_unused:UNUSED_PAD src0_sel:WORD_1
	v_pk_mul_f32 v[142:143], v[142:143], s[8:9] op_sel_hi:[1,0]
	s_nop 0
	v_pk_fma_f32 v[88:89], v[88:89], v[172:173], v[142:143]
	v_pk_mul_f32 v[140:141], v[140:141], s[8:9] op_sel_hi:[1,0]
	s_nop 0
	v_pk_fma_f32 v[90:91], v[90:91], v[170:171], v[140:141]
	v_add_u32_e32 v140, v149, v180
	ds_read_b64 v[140:141], v140
	s_waitcnt lgkmcnt(0)
	v_cvt_f32_f16_e32 v142, v140
	v_cvt_f32_f16_sdwa v143, v140 dst_sel:DWORD dst_unused:UNUSED_PAD src0_sel:WORD_1
	v_cvt_f32_f16_e32 v140, v141
	v_cvt_f32_f16_sdwa v141, v141 dst_sel:DWORD dst_unused:UNUSED_PAD src0_sel:WORD_1
	v_pk_mul_f32 v[142:143], v[142:143], s[8:9] op_sel_hi:[1,0]
	s_nop 0
	v_pk_fma_f32 v[84:85], v[84:85], v[168:169], v[142:143]
	v_pk_mul_f32 v[140:141], v[140:141], s[8:9] op_sel_hi:[1,0]
	s_nop 0
	v_pk_fma_f32 v[86:87], v[86:87], v[166:167], v[140:141]
	v_add_u32_e32 v140, v149, v148
	ds_read_b64 v[140:141], v140
	s_waitcnt lgkmcnt(0)
	v_cvt_f32_f16_e32 v142, v140
	v_cvt_f32_f16_sdwa v143, v140 dst_sel:DWORD dst_unused:UNUSED_PAD src0_sel:WORD_1
	v_cvt_f32_f16_e32 v140, v141
	v_cvt_f32_f16_sdwa v141, v141 dst_sel:DWORD dst_unused:UNUSED_PAD src0_sel:WORD_1
	v_pk_mul_f32 v[142:143], v[142:143], s[8:9] op_sel_hi:[1,0]
	s_nop 0
	v_pk_fma_f32 v[80:81], v[80:81], v[164:165], v[142:143]
	v_pk_mul_f32 v[140:141], v[140:141], s[8:9] op_sel_hi:[1,0]
	s_nop 0
	v_pk_fma_f32 v[82:83], v[82:83], v[162:163], v[140:141]
	v_add_u32_e32 v140, 0x12000, v184
	v_and_b32_e32 v140, 0xffffbc00, v140
	v_add_u32_e32 v149, v183, v140
	v_add_u32_e32 v140, v149, v182
	ds_read_b64 v[140:141], v140
	s_waitcnt lgkmcnt(0)
	v_cvt_f32_f16_e32 v142, v140
	v_cvt_f32_f16_sdwa v143, v140 dst_sel:DWORD dst_unused:UNUSED_PAD src0_sel:WORD_1
	v_cvt_f32_f16_e32 v140, v141
	v_cvt_f32_f16_sdwa v141, v141 dst_sel:DWORD dst_unused:UNUSED_PAD src0_sel:WORD_1
	v_pk_mul_f32 v[142:143], v[142:143], s[8:9] op_sel_hi:[1,0]
	s_nop 0
	v_pk_fma_f32 v[76:77], v[76:77], v[176:177], v[142:143]
	v_pk_mul_f32 v[140:141], v[140:141], s[8:9] op_sel_hi:[1,0]
	s_nop 0
	v_pk_fma_f32 v[78:79], v[78:79], v[174:175], v[140:141]
	v_add_u32_e32 v140, v149, v156
	ds_read_b64 v[140:141], v140
	s_waitcnt lgkmcnt(0)
	v_cvt_f32_f16_e32 v142, v140
	v_cvt_f32_f16_sdwa v143, v140 dst_sel:DWORD dst_unused:UNUSED_PAD src0_sel:WORD_1
	v_cvt_f32_f16_e32 v140, v141
	v_cvt_f32_f16_sdwa v141, v141 dst_sel:DWORD dst_unused:UNUSED_PAD src0_sel:WORD_1
	v_pk_mul_f32 v[142:143], v[142:143], s[8:9] op_sel_hi:[1,0]
	s_nop 0
	v_pk_fma_f32 v[72:73], v[72:73], v[172:173], v[142:143]
	v_pk_mul_f32 v[140:141], v[140:141], s[8:9] op_sel_hi:[1,0]
	s_nop 0
	v_pk_fma_f32 v[74:75], v[74:75], v[170:171], v[140:141]
	v_add_u32_e32 v140, v149, v180
	ds_read_b64 v[140:141], v140
	s_waitcnt lgkmcnt(0)
	v_cvt_f32_f16_e32 v142, v140
	v_cvt_f32_f16_sdwa v143, v140 dst_sel:DWORD dst_unused:UNUSED_PAD src0_sel:WORD_1
	v_cvt_f32_f16_e32 v140, v141
	v_cvt_f32_f16_sdwa v141, v141 dst_sel:DWORD dst_unused:UNUSED_PAD src0_sel:WORD_1
	v_pk_mul_f32 v[142:143], v[142:143], s[8:9] op_sel_hi:[1,0]
	s_nop 0
	v_pk_fma_f32 v[68:69], v[68:69], v[168:169], v[142:143]
	v_pk_mul_f32 v[140:141], v[140:141], s[8:9] op_sel_hi:[1,0]
	s_nop 0
	v_pk_fma_f32 v[70:71], v[70:71], v[166:167], v[140:141]
	v_add_u32_e32 v140, v149, v148
	ds_read_b64 v[140:141], v140
	v_add_u32_e32 v149, 0x14000, v181
	s_waitcnt lgkmcnt(0)
	v_cvt_f32_f16_e32 v142, v140
	v_cvt_f32_f16_sdwa v143, v140 dst_sel:DWORD dst_unused:UNUSED_PAD src0_sel:WORD_1
	v_cvt_f32_f16_e32 v140, v141
	v_cvt_f32_f16_sdwa v141, v141 dst_sel:DWORD dst_unused:UNUSED_PAD src0_sel:WORD_1
	v_pk_mul_f32 v[142:143], v[142:143], s[8:9] op_sel_hi:[1,0]
	s_nop 0
	v_pk_fma_f32 v[64:65], v[64:65], v[164:165], v[142:143]
	v_pk_mul_f32 v[140:141], v[140:141], s[8:9] op_sel_hi:[1,0]
	s_nop 0
	v_pk_fma_f32 v[66:67], v[66:67], v[162:163], v[140:141]
	v_add_u32_e32 v140, v149, v182
	ds_read_b64 v[140:141], v140
	s_waitcnt lgkmcnt(0)
	v_cvt_f32_f16_e32 v142, v140
	v_cvt_f32_f16_sdwa v143, v140 dst_sel:DWORD dst_unused:UNUSED_PAD src0_sel:WORD_1
	v_cvt_f32_f16_e32 v140, v141
	v_cvt_f32_f16_sdwa v141, v141 dst_sel:DWORD dst_unused:UNUSED_PAD src0_sel:WORD_1
	v_pk_mul_f32 v[142:143], v[142:143], s[8:9] op_sel_hi:[1,0]
	s_nop 0
	v_pk_fma_f32 v[60:61], v[60:61], v[176:177], v[142:143]
	v_pk_mul_f32 v[140:141], v[140:141], s[8:9] op_sel_hi:[1,0]
	s_nop 0
	v_pk_fma_f32 v[62:63], v[62:63], v[174:175], v[140:141]
	v_add_u32_e32 v140, v149, v156
	ds_read_b64 v[140:141], v140
	s_waitcnt lgkmcnt(0)
	v_cvt_f32_f16_e32 v142, v140
	v_cvt_f32_f16_sdwa v143, v140 dst_sel:DWORD dst_unused:UNUSED_PAD src0_sel:WORD_1
	v_cvt_f32_f16_e32 v140, v141
	v_cvt_f32_f16_sdwa v141, v141 dst_sel:DWORD dst_unused:UNUSED_PAD src0_sel:WORD_1
	v_pk_mul_f32 v[142:143], v[142:143], s[8:9] op_sel_hi:[1,0]
	s_nop 0
	v_pk_fma_f32 v[56:57], v[56:57], v[172:173], v[142:143]
	v_pk_mul_f32 v[140:141], v[140:141], s[8:9] op_sel_hi:[1,0]
	s_nop 0
	v_pk_fma_f32 v[58:59], v[58:59], v[170:171], v[140:141]
	v_add_u32_e32 v140, v149, v180
	ds_read_b64 v[140:141], v140
	s_waitcnt lgkmcnt(0)
	v_cvt_f32_f16_e32 v142, v140
	v_cvt_f32_f16_sdwa v143, v140 dst_sel:DWORD dst_unused:UNUSED_PAD src0_sel:WORD_1
	v_cvt_f32_f16_e32 v140, v141
	v_cvt_f32_f16_sdwa v141, v141 dst_sel:DWORD dst_unused:UNUSED_PAD src0_sel:WORD_1
	v_pk_mul_f32 v[142:143], v[142:143], s[8:9] op_sel_hi:[1,0]
	s_nop 0
	v_pk_fma_f32 v[52:53], v[52:53], v[168:169], v[142:143]
	v_pk_mul_f32 v[140:141], v[140:141], s[8:9] op_sel_hi:[1,0]
	s_nop 0
	v_pk_fma_f32 v[54:55], v[54:55], v[166:167], v[140:141]
	v_add_u32_e32 v140, v149, v148
	ds_read_b64 v[140:141], v140
	v_add_u32_e32 v149, 0x16000, v181
	s_waitcnt lgkmcnt(0)
	v_cvt_f32_f16_e32 v142, v140
	v_cvt_f32_f16_sdwa v143, v140 dst_sel:DWORD dst_unused:UNUSED_PAD src0_sel:WORD_1
	v_cvt_f32_f16_e32 v140, v141
	v_cvt_f32_f16_sdwa v141, v141 dst_sel:DWORD dst_unused:UNUSED_PAD src0_sel:WORD_1
	v_pk_mul_f32 v[142:143], v[142:143], s[8:9] op_sel_hi:[1,0]
	s_nop 0
	v_pk_fma_f32 v[48:49], v[48:49], v[164:165], v[142:143]
	v_pk_mul_f32 v[140:141], v[140:141], s[8:9] op_sel_hi:[1,0]
	s_nop 0
	v_pk_fma_f32 v[50:51], v[50:51], v[162:163], v[140:141]
	v_add_u32_e32 v140, v149, v182
	ds_read_b64 v[140:141], v140
	s_waitcnt lgkmcnt(0)
	v_cvt_f32_f16_e32 v142, v140
	v_cvt_f32_f16_sdwa v143, v140 dst_sel:DWORD dst_unused:UNUSED_PAD src0_sel:WORD_1
	v_cvt_f32_f16_e32 v140, v141
	v_cvt_f32_f16_sdwa v141, v141 dst_sel:DWORD dst_unused:UNUSED_PAD src0_sel:WORD_1
	v_pk_mul_f32 v[142:143], v[142:143], s[8:9] op_sel_hi:[1,0]
	s_nop 0
	v_pk_fma_f32 v[44:45], v[44:45], v[176:177], v[142:143]
	v_pk_mul_f32 v[140:141], v[140:141], s[8:9] op_sel_hi:[1,0]
	s_nop 0
	v_pk_fma_f32 v[46:47], v[46:47], v[174:175], v[140:141]
	v_add_u32_e32 v140, v149, v156
	ds_read_b64 v[140:141], v140
	s_waitcnt lgkmcnt(0)
	v_cvt_f32_f16_e32 v142, v140
	v_cvt_f32_f16_sdwa v143, v140 dst_sel:DWORD dst_unused:UNUSED_PAD src0_sel:WORD_1
	v_cvt_f32_f16_e32 v140, v141
	v_cvt_f32_f16_sdwa v141, v141 dst_sel:DWORD dst_unused:UNUSED_PAD src0_sel:WORD_1
	v_pk_mul_f32 v[142:143], v[142:143], s[8:9] op_sel_hi:[1,0]
	s_nop 0
	v_pk_fma_f32 v[40:41], v[40:41], v[172:173], v[142:143]
	v_pk_mul_f32 v[140:141], v[140:141], s[8:9] op_sel_hi:[1,0]
	s_nop 0
	v_pk_fma_f32 v[42:43], v[42:43], v[170:171], v[140:141]
	v_add_u32_e32 v140, v149, v180
	ds_read_b64 v[140:141], v140
	s_waitcnt lgkmcnt(0)
	v_cvt_f32_f16_e32 v142, v140
	v_cvt_f32_f16_sdwa v143, v140 dst_sel:DWORD dst_unused:UNUSED_PAD src0_sel:WORD_1
	v_cvt_f32_f16_e32 v140, v141
	v_cvt_f32_f16_sdwa v141, v141 dst_sel:DWORD dst_unused:UNUSED_PAD src0_sel:WORD_1
	v_pk_mul_f32 v[142:143], v[142:143], s[8:9] op_sel_hi:[1,0]
	s_nop 0
	v_pk_fma_f32 v[36:37], v[36:37], v[168:169], v[142:143]
	v_pk_mul_f32 v[140:141], v[140:141], s[8:9] op_sel_hi:[1,0]
	v_xor_b32_e32 v169, 64, v20
	v_pk_fma_f32 v[38:39], v[38:39], v[166:167], v[140:141]
	v_add_u32_e32 v140, v149, v148
	ds_read_b64 v[140:141], v140
	v_pk_add_f32 v[148:149], v[2:3], v[22:23]
	v_xor_b32_e32 v168, 0x80, v20
	v_pk_mov_b32 v[20:21], v[154:155], v[152:153] op_sel:[1,0]
	v_mov_b32_e32 v22, v154
	s_waitcnt lgkmcnt(0)
	v_cvt_f32_f16_e32 v142, v140
	v_cvt_f32_f16_sdwa v143, v140 dst_sel:DWORD dst_unused:UNUSED_PAD src0_sel:WORD_1
	v_cvt_f32_f16_e32 v140, v141
	v_cvt_f32_f16_sdwa v141, v141 dst_sel:DWORD dst_unused:UNUSED_PAD src0_sel:WORD_1
	v_mov_b32_e32 v23, v153
	v_pk_mul_f32 v[142:143], v[142:143], s[8:9] op_sel_hi:[1,0]
	v_pk_add_f32 v[20:21], v[20:21], v[22:23]
	v_pk_fma_f32 v[32:33], v[32:33], v[164:165], v[142:143]
	v_pk_add_f32 v[142:143], v[12:13], v[28:29]
	v_pk_mov_b32 v[22:23], v[150:151], v[148:149] op_sel:[1,0]
	v_mov_b32_e32 v28, v150
	v_mov_b32_e32 v29, v149
	v_pk_mul_f32 v[140:141], v[140:141], s[8:9] op_sel_hi:[1,0]
	v_pk_add_f32 v[22:23], v[22:23], v[28:29]
	v_pk_fma_f32 v[34:35], v[34:35], v[162:163], v[140:141]
	v_pk_add_f32 v[140:141], v[14:15], v[30:31]
	v_add_f32_e32 v20, v20, v21
	v_pk_add_f32 v[22:23], v[22:23], v[22:23] op_sel_hi:[0,1]
	v_add_f32_e32 v21, 0, v20
	v_add_f32_e32 v29, v142, v143
	v_add_f32_e32 v31, v140, v141
	v_mov_b32_e32 v28, v18
	v_mov_b32_e32 v30, v19
	v_mov_b32_e32 v22, v16
	v_mov_b32_e32 v20, v17
	v_pk_add_f32 v[28:29], v[28:29], v[30:31]
	v_pk_add_f32 v[20:21], v[22:23], v[20:21]
	s_waitcnt lgkmcnt(0)
	s_barrier
	v_pk_add_f32 v[20:21], v[28:29], v[20:21]
	s_nop 0
	v_add_f32_e32 v20, v20, v21
	s_mov_b32 s100, 0xffff0000
	s_mov_b32 s101, 0xffff0000
	s_mov_b32 s98, 0
	s_mov_b32 s99, -1
	v_mov_b32_e32 v21, v20
	v_mov_b32_e32 v210, v20
	s_nop 1
	v_permlane16_swap_b32_e32 v21, v210
	v_cndmask_b32_e64 v21, v210, v21, s[100:101]
	s_waitcnt lgkmcnt(0)
	v_add_f32_e32 v20, v20, v21
	v_mov_b32_e32 v21, v20
	v_mov_b32_e32 v210, v20
	s_nop 1
	v_permlane32_swap_b32_e32 v21, v210
	v_cndmask_b32_e64 v21, v210, v21, s[98:99]
	s_waitcnt lgkmcnt(0)
	v_add_f32_e32 v20, v20, v21
	v_fmamk_f32 v22, v20, 0xbc800000, v153
	v_fmamk_f32 v28, v20, 0xbc800000, v155
	v_fmamk_f32 v21, v20, 0xbc800000, v152
	v_fmamk_f32 v23, v20, 0xbc800000, v154
	v_mul_f32_e32 v28, v28, v28
	v_mul_f32_e32 v22, v22, v22
	v_fmac_f32_e32 v28, v23, v23
	v_fmac_f32_e32 v22, v21, v21
	v_fmamk_f32 v23, v20, 0xbc800000, v149
	v_fmamk_f32 v29, v20, 0xbc800000, v151
	v_add_f32_e32 v21, v28, v22
	v_fmamk_f32 v22, v20, 0xbc800000, v148
	v_fmamk_f32 v28, v20, 0xbc800000, v150
	v_mul_f32_e32 v29, v29, v29
	v_mul_f32_e32 v23, v23, v23
	v_fmac_f32_e32 v29, v28, v28
	v_fmac_f32_e32 v23, v22, v22
	v_add_f32_e32 v22, v29, v23
	v_fmamk_f32 v23, v20, 0xbc800000, v141
	v_fmamk_f32 v29, v20, 0xbc800000, v143
	v_add_f32_e32 v21, v21, v22
	v_fmamk_f32 v22, v20, 0xbc800000, v140
	v_fmamk_f32 v28, v20, 0xbc800000, v142
	v_mul_f32_e32 v29, v29, v29
	v_mul_f32_e32 v23, v23, v23
	v_fmac_f32_e32 v29, v28, v28
	v_fmac_f32_e32 v23, v22, v22
	v_add_f32_e32 v22, v29, v23
	v_fmamk_f32 v23, v20, 0xbc800000, v17
	v_fmamk_f32 v29, v20, 0xbc800000, v19
	v_add_f32_e32 v21, v22, v21
	v_fmamk_f32 v22, v20, 0xbc800000, v16
	v_fmamk_f32 v28, v20, 0xbc800000, v18
	v_mul_f32_e32 v29, v29, v29
	v_mul_f32_e32 v23, v23, v23
	v_fmac_f32_e32 v29, v28, v28
	v_fmac_f32_e32 v23, v22, v22
	v_add_f32_e32 v22, v29, v23
	v_add_f32_e32 v21, v22, v21
	v_mov_b32_e32 v22, v21
	v_mov_b32_e32 v210, v21
	s_nop 1
	v_permlane16_swap_b32_e32 v22, v210
	v_cndmask_b32_e64 v22, v210, v22, s[100:101]
	s_waitcnt lgkmcnt(0)
	v_add_f32_e32 v21, v21, v22
	v_mov_b32_e32 v22, v21
	v_mov_b32_e32 v210, v21
	s_nop 1
	v_permlane32_swap_b32_e32 v22, v210
	v_cndmask_b32_e64 v22, v210, v22, s[98:99]
	s_and_saveexec_b64 s[8:9], vcc
	s_cbranch_execz .LBB0_853
	s_lshl_b32 s3, s24, 11
	s_add_i32 s3, s11, s3
	v_mul_f32_e32 v20, 0x3c800000, v20
	s_waitcnt lgkmcnt(0)
	v_add_f32_e32 v21, v21, v22
	v_lshl_add_u32 v22, v178, 5, s3
	ds_write_b64 v22, v[20:21]

.LBB0_1003:
	v_lshl_add_u64 v[20:21], v[160:161], 2, s[18:19]
	global_load_dwordx4 v[196:199], v[20:21], off
	global_load_dwordx4 v[200:203], v[20:21], off offset:64
	global_load_dwordx4 v[204:207], v[20:21], off offset:512
	global_load_dwordx4 v[208:211], v[20:21], off offset:576
	s_mov_b32 s8, 0x3a800000
	s_lshl_b32 s10, s23, 5
	v_readlane_b32 s3, v254, 17
	s_add_i32 s3, s3, s10
	s_lshl_b32 s11, s5, 2
	v_cmp_gt_u32_e32 vcc, 16, v178
	v_mbcnt_lo_u32_b32 v30, -1, 0
	v_mbcnt_hi_u32_b32 v30, -1, v30
	v_ashrrev_i32_e32 v31, 5, v30
	v_add_u32_e32 v16, s3, v31
	v_and_b32_e32 v180, 31, v30
	v_ashrrev_i32_e32 v17, 31, v16
	v_readlane_b32 s8, v253, 47
	v_lshlrev_b64 v[16:17], 11, v[16:17]
	v_readlane_b32 s9, v253, 48
	s_lshl_b32 s3, s23, 14
	v_bitop3_b32 v18, v31, v180, 15 bitop3:0x6c
	v_lshl_add_u64 v[16:17], s[8:9], 0, v[16:17]
	s_add_i32 s3, s3, 0
	v_lshlrev_b32_e32 v230, 4, v18
	v_lshl_add_u64 v[18:19], v[16:17], 0, v[230:231]
	s_mov_b32 m0, s3
	s_mov_b64 s[8:9], 0x1000
	global_load_lds_dwordx4 v[18:19], off
	v_lshl_add_u64 v[18:19], v[16:17], 0, s[8:9]
	v_add_u32_e32 v16, 2, v31
	v_bitop3_b32 v16, v16, v180, 15 bitop3:0x6c
	v_lshlrev_b32_e32 v16, 4, v16
	v_mov_b32_e32 v17, v231
	s_add_i32 m0, s3, 0x400
	v_lshl_add_u64 v[20:21], v[18:19], 0, v[16:17]
	global_load_lds_dwordx4 v[20:21], off
	v_lshl_add_u64 v[20:21], v[18:19], 0, s[8:9]
	v_add_u32_e32 v18, 4, v31
	v_bitop3_b32 v18, v18, v180, 15 bitop3:0x6c
	v_lshlrev_b32_e32 v18, 4, v18
	v_mov_b32_e32 v19, v231
	s_add_i32 m0, s3, 0x800
	v_lshl_add_u64 v[22:23], v[20:21], 0, v[18:19]
	global_load_lds_dwordx4 v[22:23], off
	v_lshl_add_u64 v[22:23], v[20:21], 0, s[8:9]
	v_add_u32_e32 v20, 6, v31
	v_bitop3_b32 v20, v20, v180, 15 bitop3:0x6c
	v_lshlrev_b32_e32 v20, 4, v20
	v_mov_b32_e32 v21, v231
	s_add_i32 m0, s3, 0xc00
	v_lshl_add_u64 v[24:25], v[22:23], 0, v[20:21]
	global_load_lds_dwordx4 v[24:25], off
	v_lshl_add_u64 v[24:25], v[22:23], 0, s[8:9]
	v_xor_b32_e32 v22, 0x80, v230
	v_mov_b32_e32 v23, v231
	s_add_i32 m0, s3, 0x1000
	v_lshl_add_u64 v[26:27], v[24:25], 0, v[22:23]
	global_load_lds_dwordx4 v[26:27], off
	v_lshl_add_u64 v[26:27], v[24:25], 0, s[8:9]
	v_add_u32_e32 v24, 10, v31
	v_bitop3_b32 v24, v24, v180, 15 bitop3:0x6c
	v_lshlrev_b32_e32 v24, 4, v24
	v_mov_b32_e32 v25, v231
	s_add_i32 m0, s3, 0x1400
	v_lshl_add_u64 v[28:29], v[26:27], 0, v[24:25]
	global_load_lds_dwordx4 v[28:29], off
	v_add_u32_e32 v28, 12, v31
	v_lshl_add_u64 v[26:27], v[26:27], 0, s[8:9]
	v_bitop3_b32 v28, v28, v180, 15 bitop3:0x6c
	v_lshlrev_b32_e32 v28, 4, v28
	v_mov_b32_e32 v29, v231
	v_add_u32_e32 v181, 14, v31
	v_lshl_add_u64 v[182:183], v[26:27], 0, v[28:29]
	s_add_i32 m0, s3, 0x1800
	v_lshl_add_u64 v[26:27], v[26:27], 0, s[8:9]
	v_bitop3_b32 v180, v181, v180, 15 bitop3:0x6c
	global_load_lds_dwordx4 v[182:183], off
	v_lshlrev_b32_e32 v180, 4, v180
	v_mov_b32_e32 v181, v231
	v_lshl_add_u64 v[182:183], v[26:27], 0, v[180:181]
	s_add_i32 m0, s3, 0x1c00
	v_lshl_add_u64 v[26:27], v[26:27], 0, s[8:9]
	global_load_lds_dwordx4 v[182:183], off
	s_add_i32 m0, s3, 0x2000
	v_lshl_add_u64 v[182:183], v[26:27], 0, v[230:231]
	v_lshl_add_u64 v[26:27], v[26:27], 0, s[8:9]
	global_load_lds_dwordx4 v[182:183], off
	s_add_i32 m0, s3, 0x2400
	v_lshl_add_u64 v[16:17], v[26:27], 0, v[16:17]
	global_load_lds_dwordx4 v[16:17], off
	v_lshl_add_u64 v[16:17], v[26:27], 0, s[8:9]
	s_add_i32 m0, s3, 0x2800
	v_lshl_add_u64 v[18:19], v[16:17], 0, v[18:19]
	v_lshl_add_u64 v[16:17], v[16:17], 0, s[8:9]
	global_load_lds_dwordx4 v[18:19], off
	s_add_i32 m0, s3, 0x2c00
	v_lshl_add_u64 v[18:19], v[16:17], 0, v[20:21]
	v_lshl_add_u64 v[16:17], v[16:17], 0, s[8:9]
	global_load_lds_dwordx4 v[18:19], off
	s_add_i32 m0, s3, 0x3000
	v_lshl_add_u64 v[18:19], v[16:17], 0, v[22:23]
	v_lshl_add_u64 v[16:17], v[16:17], 0, s[8:9]
	global_load_lds_dwordx4 v[18:19], off
	s_add_i32 m0, s3, 0x3400
	v_lshl_add_u64 v[18:19], v[16:17], 0, v[24:25]
	v_lshl_add_u64 v[16:17], v[16:17], 0, s[8:9]
	global_load_lds_dwordx4 v[18:19], off
	s_add_i32 m0, s3, 0x3800
	v_lshl_add_u64 v[18:19], v[16:17], 0, v[28:29]
	v_lshl_add_u64 v[16:17], v[16:17], 0, s[8:9]
	global_load_lds_dwordx4 v[18:19], off
	s_add_i32 m0, s3, 0x3c00
	v_lshl_add_u64 v[18:19], v[16:17], 0, v[180:181]
	v_lshl_add_u64 v[16:17], v[16:17], 0, s[8:9]
	global_load_lds_dwordx4 v[18:19], off
	v_lshrrev_b32_e32 v18, 1, v30
	v_lshlrev_b32_e32 v17, 9, v30
	v_and_b32_e32 v17, 0x200, v17
	v_and_b32_e32 v18, 8, v18
	v_add_u32_e32 v28, s11, v31
	v_and_b32_e32 v16, 15, v30
	v_add3_u32 v183, 0, v17, v18
	v_add_u32_e32 v17, 16, v28
	v_bitop3_b32 v17, v17, v30, 15 bitop3:0x78
	s_lshl_b32 s3, s22, 15
	v_lshlrev_b32_e32 v16, 9, v16
	v_lshlrev_b32_e32 v180, 4, v17
	v_or_b32_e32 v184, s3, v16
	v_mov_b32_e32 v17, s3
	s_movk_i32 s3, 0x9c00
	v_bitop3_b32 v16, v16, s3, v17 bitop3:0xc8
	v_add_u32_e32 v181, v183, v16
	v_bitop3_b32 v16, v28, v30, 15 bitop3:0x78
	v_lshlrev_b32_e32 v182, 4, v16
	s_waitcnt vmcnt(0)
	s_mov_b32 s100, 0x3a800000
	v_pk_mul_f32 v[174:175], v[198:199], s[100:101] op_sel_hi:[1,0]
	v_pk_mul_f32 v[176:177], v[196:197], s[100:101] op_sel_hi:[1,0]
	v_pk_mul_f32 v[170:171], v[202:203], s[100:101] op_sel_hi:[1,0]
	v_pk_mul_f32 v[172:173], v[200:201], s[100:101] op_sel_hi:[1,0]
	v_pk_mul_f32 v[166:167], v[206:207], s[100:101] op_sel_hi:[1,0]
	v_pk_mul_f32 v[168:169], v[204:205], s[100:101] op_sel_hi:[1,0]
	v_pk_mul_f32 v[164:165], v[208:209], s[100:101] op_sel_hi:[1,0]
	v_pk_mul_f32 v[162:163], v[210:211], s[100:101] op_sel_hi:[1,0]
	s_barrier
	v_add_u32_e32 v185, v181, v182
	ds_read_b64 v[16:17], v185
	s_mov_b32 s8, 0x3fd744fd
	s_lshl_b32 s3, s5, 3
	s_add_i32 s12, s3, 0
	s_waitcnt lgkmcnt(0)
	v_cvt_f32_f16_e32 v18, v16
	v_cvt_f32_f16_sdwa v19, v16 dst_sel:DWORD dst_unused:UNUSED_PAD src0_sel:WORD_1
	v_cvt_f32_f16_e32 v16, v17
	v_cvt_f32_f16_sdwa v17, v17 dst_sel:DWORD dst_unused:UNUSED_PAD src0_sel:WORD_1
	v_pk_mul_f32 v[20:21], v[18:19], s[8:9] op_sel_hi:[1,0]
	v_pk_mul_f32 v[16:17], v[16:17], s[8:9] op_sel_hi:[1,0]
	s_nop 0
	v_pk_fma_f32 v[18:19], v[158:159], v[174:175], v[16:17]
	v_pk_fma_f32 v[16:17], v[156:157], v[176:177], v[20:21]
	v_add_u32_e32 v20, 2, v28
	v_bitop3_b32 v20, v20, v30, 15 bitop3:0x78
	v_lshlrev_b32_e32 v156, 4, v20
	v_add_u32_e32 v157, v181, v156
	ds_read_b64 v[20:21], v157
	s_waitcnt lgkmcnt(0)
	v_cvt_f32_f16_e32 v22, v20
	v_cvt_f32_f16_sdwa v23, v20 dst_sel:DWORD dst_unused:UNUSED_PAD src0_sel:WORD_1
	v_cvt_f32_f16_e32 v20, v21
	v_cvt_f32_f16_sdwa v21, v21 dst_sel:DWORD dst_unused:UNUSED_PAD src0_sel:WORD_1
	v_pk_mul_f32 v[22:23], v[22:23], s[8:9] op_sel_hi:[1,0]
	s_nop 0
	v_pk_fma_f32 v[24:25], v[152:153], v[172:173], v[22:23]
	v_pk_mul_f32 v[20:21], v[20:21], s[8:9] op_sel_hi:[1,0]
	v_add_u32_e32 v153, v181, v180
	v_pk_fma_f32 v[26:27], v[154:155], v[170:171], v[20:21]
	ds_read_b64 v[20:21], v153
	s_waitcnt lgkmcnt(0)
	v_cvt_f32_f16_e32 v22, v20
	v_cvt_f32_f16_sdwa v23, v20 dst_sel:DWORD dst_unused:UNUSED_PAD src0_sel:WORD_1
	v_cvt_f32_f16_e32 v20, v21
	v_cvt_f32_f16_sdwa v21, v21 dst_sel:DWORD dst_unused:UNUSED_PAD src0_sel:WORD_1
	v_pk_mul_f32 v[22:23], v[22:23], s[8:9] op_sel_hi:[1,0]
	s_nop 0
	v_pk_fma_f32 v[148:149], v[148:149], v[168:169], v[22:23]
	v_pk_mul_f32 v[20:21], v[20:21], s[8:9] op_sel_hi:[1,0]
	s_nop 0
	v_pk_fma_f32 v[150:151], v[150:151], v[166:167], v[20:21]
	v_add_u32_e32 v20, 18, v28
	v_bitop3_b32 v20, v20, v30, 15 bitop3:0x78
	v_lshlrev_b32_e32 v152, 4, v20
	v_add_u32_e32 v154, v181, v152
	ds_read_b64 v[20:21], v154
	s_waitcnt lgkmcnt(0)
	v_cvt_f32_f16_e32 v22, v20
	v_cvt_f32_f16_sdwa v23, v20 dst_sel:DWORD dst_unused:UNUSED_PAD src0_sel:WORD_1
	v_cvt_f32_f16_e32 v20, v21
	v_cvt_f32_f16_sdwa v21, v21 dst_sel:DWORD dst_unused:UNUSED_PAD src0_sel:WORD_1
	v_pk_mul_f32 v[22:23], v[22:23], s[8:9] op_sel_hi:[1,0]
	s_nop 0
	v_pk_fma_f32 v[144:145], v[144:145], v[164:165], v[22:23]
	v_pk_mul_f32 v[20:21], v[20:21], s[8:9] op_sel_hi:[1,0]
	s_nop 0
	v_pk_fma_f32 v[146:147], v[146:147], v[162:163], v[20:21]
	s_nop 0
	ds_read_b64 v[20:21], v185 offset:8192
	s_waitcnt lgkmcnt(0)
	v_cvt_f32_f16_e32 v22, v20
	v_cvt_f32_f16_sdwa v23, v20 dst_sel:DWORD dst_unused:UNUSED_PAD src0_sel:WORD_1
	v_cvt_f32_f16_e32 v20, v21
	v_cvt_f32_f16_sdwa v21, v21 dst_sel:DWORD dst_unused:UNUSED_PAD src0_sel:WORD_1
	v_pk_mul_f32 v[28:29], v[22:23], s[8:9] op_sel_hi:[1,0]
	v_pk_mul_f32 v[20:21], v[20:21], s[8:9] op_sel_hi:[1,0]
	s_nop 0
	v_pk_fma_f32 v[22:23], v[142:143], v[174:175], v[20:21]
	v_pk_fma_f32 v[20:21], v[140:141], v[176:177], v[28:29]
	ds_read_b64 v[28:29], v157 offset:8192
	v_pk_add_f32 v[142:143], v[0:1], v[24:25]
	v_lshlrev_b32_e32 v24, 2, v178
	s_waitcnt lgkmcnt(0)
	v_cvt_f32_f16_e32 v30, v28
	v_cvt_f32_f16_sdwa v31, v28 dst_sel:DWORD dst_unused:UNUSED_PAD src0_sel:WORD_1
	v_cvt_f32_f16_e32 v28, v29
	v_cvt_f32_f16_sdwa v29, v29 dst_sel:DWORD dst_unused:UNUSED_PAD src0_sel:WORD_1
	v_pk_mul_f32 v[140:141], v[30:31], s[8:9] op_sel_hi:[1,0]
	v_pk_mul_f32 v[28:29], v[28:29], s[8:9] op_sel_hi:[1,0]
	s_nop 0
	v_pk_fma_f32 v[30:31], v[138:139], v[170:171], v[28:29]
	v_pk_fma_f32 v[28:29], v[136:137], v[172:173], v[140:141]
	ds_read_b64 v[136:137], v153 offset:8192
	v_add_u32_e32 v140, 0x10000, v181
	s_waitcnt lgkmcnt(0)
	v_cvt_f32_f16_e32 v138, v136
	v_cvt_f32_f16_sdwa v139, v136 dst_sel:DWORD dst_unused:UNUSED_PAD src0_sel:WORD_1
	v_cvt_f32_f16_e32 v136, v137
	v_cvt_f32_f16_sdwa v137, v137 dst_sel:DWORD dst_unused:UNUSED_PAD src0_sel:WORD_1
	v_pk_mul_f32 v[138:139], v[138:139], s[8:9] op_sel_hi:[1,0]
	s_nop 0
	v_pk_fma_f32 v[132:133], v[132:133], v[168:169], v[138:139]
	v_pk_mul_f32 v[136:137], v[136:137], s[8:9] op_sel_hi:[1,0]
	s_nop 0
	v_pk_fma_f32 v[134:135], v[134:135], v[166:167], v[136:137]
	ds_read_b64 v[136:137], v154 offset:8192
	s_waitcnt lgkmcnt(0)
	v_cvt_f32_f16_e32 v138, v136
	v_cvt_f32_f16_sdwa v139, v136 dst_sel:DWORD dst_unused:UNUSED_PAD src0_sel:WORD_1
	v_cvt_f32_f16_e32 v136, v137
	v_cvt_f32_f16_sdwa v137, v137 dst_sel:DWORD dst_unused:UNUSED_PAD src0_sel:WORD_1
	v_pk_mul_f32 v[138:139], v[138:139], s[8:9] op_sel_hi:[1,0]
	s_nop 0
	v_pk_fma_f32 v[128:129], v[128:129], v[164:165], v[138:139]
	v_pk_mul_f32 v[136:137], v[136:137], s[8:9] op_sel_hi:[1,0]
	s_nop 0
	v_pk_fma_f32 v[130:131], v[130:131], v[162:163], v[136:137]
	s_nop 0
	ds_read_b64 v[136:137], v185 offset:16384
	s_waitcnt lgkmcnt(0)
	v_cvt_f32_f16_e32 v138, v136
	v_cvt_f32_f16_sdwa v139, v136 dst_sel:DWORD dst_unused:UNUSED_PAD src0_sel:WORD_1
	v_cvt_f32_f16_e32 v136, v137
	v_cvt_f32_f16_sdwa v137, v137 dst_sel:DWORD dst_unused:UNUSED_PAD src0_sel:WORD_1
	v_pk_mul_f32 v[138:139], v[138:139], s[8:9] op_sel_hi:[1,0]
	s_nop 0
	v_pk_fma_f32 v[124:125], v[124:125], v[176:177], v[138:139]
	v_pk_mul_f32 v[136:137], v[136:137], s[8:9] op_sel_hi:[1,0]
	s_nop 0
	v_pk_fma_f32 v[126:127], v[126:127], v[174:175], v[136:137]
	ds_read_b64 v[136:137], v157 offset:16384
	s_waitcnt lgkmcnt(0)
	v_cvt_f32_f16_e32 v138, v136
	v_cvt_f32_f16_sdwa v139, v136 dst_sel:DWORD dst_unused:UNUSED_PAD src0_sel:WORD_1
	v_cvt_f32_f16_e32 v136, v137
	v_cvt_f32_f16_sdwa v137, v137 dst_sel:DWORD dst_unused:UNUSED_PAD src0_sel:WORD_1
	v_pk_mul_f32 v[138:139], v[138:139], s[8:9] op_sel_hi:[1,0]
	s_nop 0
	v_pk_fma_f32 v[120:121], v[120:121], v[172:173], v[138:139]
	v_pk_mul_f32 v[136:137], v[136:137], s[8:9] op_sel_hi:[1,0]
	s_nop 0
	v_pk_fma_f32 v[122:123], v[122:123], v[170:171], v[136:137]
	ds_read_b64 v[136:137], v153 offset:16384
	s_waitcnt lgkmcnt(0)
	v_cvt_f32_f16_e32 v138, v136
	v_cvt_f32_f16_sdwa v139, v136 dst_sel:DWORD dst_unused:UNUSED_PAD src0_sel:WORD_1
	v_cvt_f32_f16_e32 v136, v137
	v_cvt_f32_f16_sdwa v137, v137 dst_sel:DWORD dst_unused:UNUSED_PAD src0_sel:WORD_1
	v_pk_mul_f32 v[138:139], v[138:139], s[8:9] op_sel_hi:[1,0]
	s_nop 0
	v_pk_fma_f32 v[116:117], v[116:117], v[168:169], v[138:139]
	v_pk_mul_f32 v[136:137], v[136:137], s[8:9] op_sel_hi:[1,0]
	s_nop 0
	v_pk_fma_f32 v[118:119], v[118:119], v[166:167], v[136:137]
	ds_read_b64 v[136:137], v154 offset:16384
	s_waitcnt lgkmcnt(0)
	v_cvt_f32_f16_e32 v138, v136
	v_cvt_f32_f16_sdwa v139, v136 dst_sel:DWORD dst_unused:UNUSED_PAD src0_sel:WORD_1
	v_cvt_f32_f16_e32 v136, v137
	v_cvt_f32_f16_sdwa v137, v137 dst_sel:DWORD dst_unused:UNUSED_PAD src0_sel:WORD_1
	v_pk_mul_f32 v[138:139], v[138:139], s[8:9] op_sel_hi:[1,0]
	s_nop 0
	v_pk_fma_f32 v[112:113], v[112:113], v[164:165], v[138:139]
	v_pk_mul_f32 v[136:137], v[136:137], s[8:9] op_sel_hi:[1,0]
	s_nop 0
	v_pk_fma_f32 v[114:115], v[114:115], v[162:163], v[136:137]
	s_nop 0
	ds_read_b64 v[136:137], v185 offset:24576
	s_waitcnt lgkmcnt(0)
	v_cvt_f32_f16_e32 v138, v136
	v_cvt_f32_f16_sdwa v139, v136 dst_sel:DWORD dst_unused:UNUSED_PAD src0_sel:WORD_1
	v_cvt_f32_f16_e32 v136, v137
	v_cvt_f32_f16_sdwa v137, v137 dst_sel:DWORD dst_unused:UNUSED_PAD src0_sel:WORD_1
	v_pk_mul_f32 v[138:139], v[138:139], s[8:9] op_sel_hi:[1,0]
	s_nop 0
	v_pk_fma_f32 v[108:109], v[108:109], v[176:177], v[138:139]
	v_pk_mul_f32 v[136:137], v[136:137], s[8:9] op_sel_hi:[1,0]
	s_nop 0
	v_pk_fma_f32 v[110:111], v[110:111], v[174:175], v[136:137]
	ds_read_b64 v[136:137], v157 offset:24576
	v_xor_b32_e32 v157, 64, v24
	s_waitcnt lgkmcnt(0)
	v_cvt_f32_f16_e32 v138, v136
	v_cvt_f32_f16_sdwa v139, v136 dst_sel:DWORD dst_unused:UNUSED_PAD src0_sel:WORD_1
	v_cvt_f32_f16_e32 v136, v137
	v_cvt_f32_f16_sdwa v137, v137 dst_sel:DWORD dst_unused:UNUSED_PAD src0_sel:WORD_1
	v_pk_mul_f32 v[138:139], v[138:139], s[8:9] op_sel_hi:[1,0]
	s_nop 0
	v_pk_fma_f32 v[104:105], v[104:105], v[172:173], v[138:139]
	v_pk_mul_f32 v[136:137], v[136:137], s[8:9] op_sel_hi:[1,0]
	s_nop 0
	v_pk_fma_f32 v[106:107], v[106:107], v[170:171], v[136:137]
	ds_read_b64 v[136:137], v153 offset:24576
	s_waitcnt lgkmcnt(0)
	v_cvt_f32_f16_e32 v138, v136
	v_cvt_f32_f16_sdwa v139, v136 dst_sel:DWORD dst_unused:UNUSED_PAD src0_sel:WORD_1
	v_cvt_f32_f16_e32 v136, v137
	v_cvt_f32_f16_sdwa v137, v137 dst_sel:DWORD dst_unused:UNUSED_PAD src0_sel:WORD_1
	v_pk_mul_f32 v[138:139], v[138:139], s[8:9] op_sel_hi:[1,0]
	s_nop 0
	v_pk_fma_f32 v[100:101], v[100:101], v[168:169], v[138:139]
	v_pk_mul_f32 v[136:137], v[136:137], s[8:9] op_sel_hi:[1,0]
	s_nop 0
	v_pk_fma_f32 v[102:103], v[102:103], v[166:167], v[136:137]
	ds_read_b64 v[136:137], v154 offset:24576
	v_pk_add_f32 v[154:155], v[4:5], v[16:17]
	v_pk_add_f32 v[16:17], v[10:11], v[146:147]
	s_waitcnt lgkmcnt(0)
	v_cvt_f32_f16_e32 v138, v136
	v_cvt_f32_f16_sdwa v139, v136 dst_sel:DWORD dst_unused:UNUSED_PAD src0_sel:WORD_1
	v_cvt_f32_f16_e32 v136, v137
	v_cvt_f32_f16_sdwa v137, v137 dst_sel:DWORD dst_unused:UNUSED_PAD src0_sel:WORD_1
	v_pk_mul_f32 v[138:139], v[138:139], s[8:9] op_sel_hi:[1,0]
	s_nop 0
	v_pk_fma_f32 v[96:97], v[96:97], v[164:165], v[138:139]
	v_pk_mul_f32 v[136:137], v[136:137], s[8:9] op_sel_hi:[1,0]
	s_nop 0
	v_pk_fma_f32 v[98:99], v[98:99], v[162:163], v[136:137]
	v_add_u32_e32 v136, v140, v182
	ds_read_b64 v[136:137], v136
	s_waitcnt lgkmcnt(0)
	v_cvt_f32_f16_e32 v138, v136
	v_cvt_f32_f16_sdwa v139, v136 dst_sel:DWORD dst_unused:UNUSED_PAD src0_sel:WORD_1
	v_cvt_f32_f16_e32 v136, v137
	v_cvt_f32_f16_sdwa v137, v137 dst_sel:DWORD dst_unused:UNUSED_PAD src0_sel:WORD_1
	v_pk_mul_f32 v[138:139], v[138:139], s[8:9] op_sel_hi:[1,0]
	s_nop 0
	v_pk_fma_f32 v[92:93], v[92:93], v[176:177], v[138:139]
	v_pk_mul_f32 v[136:137], v[136:137], s[8:9] op_sel_hi:[1,0]
	s_nop 0
	v_pk_fma_f32 v[94:95], v[94:95], v[174:175], v[136:137]
	v_add_u32_e32 v136, v140, v156
	ds_read_b64 v[136:137], v136
	s_waitcnt lgkmcnt(0)
	v_cvt_f32_f16_e32 v138, v136
	v_cvt_f32_f16_sdwa v139, v136 dst_sel:DWORD dst_unused:UNUSED_PAD src0_sel:WORD_1
	v_cvt_f32_f16_e32 v136, v137
	v_cvt_f32_f16_sdwa v137, v137 dst_sel:DWORD dst_unused:UNUSED_PAD src0_sel:WORD_1
	v_pk_mul_f32 v[138:139], v[138:139], s[8:9] op_sel_hi:[1,0]
	s_nop 0
	v_pk_fma_f32 v[88:89], v[88:89], v[172:173], v[138:139]
	v_pk_mul_f32 v[136:137], v[136:137], s[8:9] op_sel_hi:[1,0]
	s_nop 0
	v_pk_fma_f32 v[90:91], v[90:91], v[170:171], v[136:137]
	v_add_u32_e32 v136, v140, v180
	ds_read_b64 v[136:137], v136
	s_waitcnt lgkmcnt(0)
	v_cvt_f32_f16_e32 v138, v136
	v_cvt_f32_f16_sdwa v139, v136 dst_sel:DWORD dst_unused:UNUSED_PAD src0_sel:WORD_1
	v_cvt_f32_f16_e32 v136, v137
	v_cvt_f32_f16_sdwa v137, v137 dst_sel:DWORD dst_unused:UNUSED_PAD src0_sel:WORD_1
	v_pk_mul_f32 v[138:139], v[138:139], s[8:9] op_sel_hi:[1,0]
	s_nop 0
	v_pk_fma_f32 v[84:85], v[84:85], v[168:169], v[138:139]
	v_pk_mul_f32 v[136:137], v[136:137], s[8:9] op_sel_hi:[1,0]
	s_nop 0
	v_pk_fma_f32 v[86:87], v[86:87], v[166:167], v[136:137]
	v_add_u32_e32 v136, v140, v152
	ds_read_b64 v[136:137], v136
	s_waitcnt lgkmcnt(0)
	v_cvt_f32_f16_e32 v138, v136
	v_cvt_f32_f16_sdwa v139, v136 dst_sel:DWORD dst_unused:UNUSED_PAD src0_sel:WORD_1
	v_cvt_f32_f16_e32 v136, v137
	v_cvt_f32_f16_sdwa v137, v137 dst_sel:DWORD dst_unused:UNUSED_PAD src0_sel:WORD_1
	v_pk_mul_f32 v[138:139], v[138:139], s[8:9] op_sel_hi:[1,0]
	s_nop 0
	v_pk_fma_f32 v[80:81], v[80:81], v[164:165], v[138:139]
	v_pk_mul_f32 v[136:137], v[136:137], s[8:9] op_sel_hi:[1,0]
	s_nop 0
	v_pk_fma_f32 v[82:83], v[82:83], v[162:163], v[136:137]
	v_add_u32_e32 v136, 0x12000, v184
	v_and_b32_e32 v136, 0xffffbc00, v136
	v_add_u32_e32 v140, v183, v136
	v_add_u32_e32 v136, v140, v182
	ds_read_b64 v[136:137], v136
	s_waitcnt lgkmcnt(0)
	v_cvt_f32_f16_e32 v138, v136
	v_cvt_f32_f16_sdwa v139, v136 dst_sel:DWORD dst_unused:UNUSED_PAD src0_sel:WORD_1
	v_cvt_f32_f16_e32 v136, v137
	v_cvt_f32_f16_sdwa v137, v137 dst_sel:DWORD dst_unused:UNUSED_PAD src0_sel:WORD_1
	v_pk_mul_f32 v[138:139], v[138:139], s[8:9] op_sel_hi:[1,0]
	s_nop 0
	v_pk_fma_f32 v[76:77], v[76:77], v[176:177], v[138:139]
	v_pk_mul_f32 v[136:137], v[136:137], s[8:9] op_sel_hi:[1,0]
	s_nop 0
	v_pk_fma_f32 v[78:79], v[78:79], v[174:175], v[136:137]
	v_add_u32_e32 v136, v140, v156
	ds_read_b64 v[136:137], v136
	s_waitcnt lgkmcnt(0)
	v_cvt_f32_f16_e32 v138, v136
	v_cvt_f32_f16_sdwa v139, v136 dst_sel:DWORD dst_unused:UNUSED_PAD src0_sel:WORD_1
	v_cvt_f32_f16_e32 v136, v137
	v_cvt_f32_f16_sdwa v137, v137 dst_sel:DWORD dst_unused:UNUSED_PAD src0_sel:WORD_1
	v_pk_mul_f32 v[138:139], v[138:139], s[8:9] op_sel_hi:[1,0]
	s_nop 0
	v_pk_fma_f32 v[72:73], v[72:73], v[172:173], v[138:139]
	v_pk_mul_f32 v[136:137], v[136:137], s[8:9] op_sel_hi:[1,0]
	s_nop 0
	v_pk_fma_f32 v[74:75], v[74:75], v[170:171], v[136:137]
	v_add_u32_e32 v136, v140, v180
	ds_read_b64 v[136:137], v136
	s_waitcnt lgkmcnt(0)
	v_cvt_f32_f16_e32 v138, v136
	v_cvt_f32_f16_sdwa v139, v136 dst_sel:DWORD dst_unused:UNUSED_PAD src0_sel:WORD_1
	v_cvt_f32_f16_e32 v136, v137
	v_cvt_f32_f16_sdwa v137, v137 dst_sel:DWORD dst_unused:UNUSED_PAD src0_sel:WORD_1
	v_pk_mul_f32 v[138:139], v[138:139], s[8:9] op_sel_hi:[1,0]
	s_nop 0
	v_pk_fma_f32 v[68:69], v[68:69], v[168:169], v[138:139]
	v_pk_mul_f32 v[136:137], v[136:137], s[8:9] op_sel_hi:[1,0]
	s_nop 0
	v_pk_fma_f32 v[70:71], v[70:71], v[166:167], v[136:137]
	v_add_u32_e32 v136, v140, v152
	ds_read_b64 v[136:137], v136
	v_add_u32_e32 v140, 0x14000, v181
	s_waitcnt lgkmcnt(0)
	v_cvt_f32_f16_e32 v138, v136
	v_cvt_f32_f16_sdwa v139, v136 dst_sel:DWORD dst_unused:UNUSED_PAD src0_sel:WORD_1
	v_cvt_f32_f16_e32 v136, v137
	v_cvt_f32_f16_sdwa v137, v137 dst_sel:DWORD dst_unused:UNUSED_PAD src0_sel:WORD_1
	v_pk_mul_f32 v[138:139], v[138:139], s[8:9] op_sel_hi:[1,0]
	s_nop 0
	v_pk_fma_f32 v[64:65], v[64:65], v[164:165], v[138:139]
	v_pk_mul_f32 v[136:137], v[136:137], s[8:9] op_sel_hi:[1,0]
	s_nop 0
	v_pk_fma_f32 v[66:67], v[66:67], v[162:163], v[136:137]
	v_add_u32_e32 v136, v140, v182
	ds_read_b64 v[136:137], v136
	s_waitcnt lgkmcnt(0)
	v_cvt_f32_f16_e32 v138, v136
	v_cvt_f32_f16_sdwa v139, v136 dst_sel:DWORD dst_unused:UNUSED_PAD src0_sel:WORD_1
	v_cvt_f32_f16_e32 v136, v137
	v_cvt_f32_f16_sdwa v137, v137 dst_sel:DWORD dst_unused:UNUSED_PAD src0_sel:WORD_1
	v_pk_mul_f32 v[138:139], v[138:139], s[8:9] op_sel_hi:[1,0]
	s_nop 0
	v_pk_fma_f32 v[60:61], v[60:61], v[176:177], v[138:139]
	v_pk_mul_f32 v[136:137], v[136:137], s[8:9] op_sel_hi:[1,0]
	s_nop 0
	v_pk_fma_f32 v[62:63], v[62:63], v[174:175], v[136:137]
	v_add_u32_e32 v136, v140, v156
	ds_read_b64 v[136:137], v136
	s_waitcnt lgkmcnt(0)
	v_cvt_f32_f16_e32 v138, v136
	v_cvt_f32_f16_sdwa v139, v136 dst_sel:DWORD dst_unused:UNUSED_PAD src0_sel:WORD_1
	v_cvt_f32_f16_e32 v136, v137
	v_cvt_f32_f16_sdwa v137, v137 dst_sel:DWORD dst_unused:UNUSED_PAD src0_sel:WORD_1
	v_pk_mul_f32 v[138:139], v[138:139], s[8:9] op_sel_hi:[1,0]
	s_nop 0
	v_pk_fma_f32 v[56:57], v[56:57], v[172:173], v[138:139]
	v_pk_mul_f32 v[136:137], v[136:137], s[8:9] op_sel_hi:[1,0]
	s_nop 0
	v_pk_fma_f32 v[58:59], v[58:59], v[170:171], v[136:137]
	v_add_u32_e32 v136, v140, v180
	ds_read_b64 v[136:137], v136
	s_waitcnt lgkmcnt(0)
	v_cvt_f32_f16_e32 v138, v136
	v_cvt_f32_f16_sdwa v139, v136 dst_sel:DWORD dst_unused:UNUSED_PAD src0_sel:WORD_1
	v_cvt_f32_f16_e32 v136, v137
	v_cvt_f32_f16_sdwa v137, v137 dst_sel:DWORD dst_unused:UNUSED_PAD src0_sel:WORD_1
	v_pk_mul_f32 v[138:139], v[138:139], s[8:9] op_sel_hi:[1,0]
	s_nop 0
	v_pk_fma_f32 v[52:53], v[52:53], v[168:169], v[138:139]
	v_pk_mul_f32 v[136:137], v[136:137], s[8:9] op_sel_hi:[1,0]
	s_nop 0
	v_pk_fma_f32 v[54:55], v[54:55], v[166:167], v[136:137]
	v_add_u32_e32 v136, v140, v152
	ds_read_b64 v[136:137], v136
	v_add_u32_e32 v140, 0x16000, v181
	s_waitcnt lgkmcnt(0)
	v_cvt_f32_f16_e32 v138, v136
	v_cvt_f32_f16_sdwa v139, v136 dst_sel:DWORD dst_unused:UNUSED_PAD src0_sel:WORD_1
	v_cvt_f32_f16_e32 v136, v137
	v_cvt_f32_f16_sdwa v137, v137 dst_sel:DWORD dst_unused:UNUSED_PAD src0_sel:WORD_1
	v_pk_mul_f32 v[138:139], v[138:139], s[8:9] op_sel_hi:[1,0]
	s_nop 0
	v_pk_fma_f32 v[48:49], v[48:49], v[164:165], v[138:139]
	v_pk_mul_f32 v[136:137], v[136:137], s[8:9] op_sel_hi:[1,0]
	s_nop 0
	v_pk_fma_f32 v[50:51], v[50:51], v[162:163], v[136:137]
	v_add_u32_e32 v136, v140, v182
	ds_read_b64 v[136:137], v136
	s_waitcnt lgkmcnt(0)
	v_cvt_f32_f16_e32 v138, v136
	v_cvt_f32_f16_sdwa v139, v136 dst_sel:DWORD dst_unused:UNUSED_PAD src0_sel:WORD_1
	v_cvt_f32_f16_e32 v136, v137
	v_cvt_f32_f16_sdwa v137, v137 dst_sel:DWORD dst_unused:UNUSED_PAD src0_sel:WORD_1
	v_pk_mul_f32 v[138:139], v[138:139], s[8:9] op_sel_hi:[1,0]
	s_nop 0
	v_pk_fma_f32 v[44:45], v[44:45], v[176:177], v[138:139]
	v_pk_mul_f32 v[136:137], v[136:137], s[8:9] op_sel_hi:[1,0]
	s_nop 0
	v_pk_fma_f32 v[46:47], v[46:47], v[174:175], v[136:137]
	v_add_u32_e32 v136, v140, v156
	ds_read_b64 v[136:137], v136
	v_xor_b32_e32 v156, 0x80, v24
	s_waitcnt lgkmcnt(0)
	v_cvt_f32_f16_e32 v138, v136
	v_cvt_f32_f16_sdwa v139, v136 dst_sel:DWORD dst_unused:UNUSED_PAD src0_sel:WORD_1
	v_cvt_f32_f16_e32 v136, v137
	v_cvt_f32_f16_sdwa v137, v137 dst_sel:DWORD dst_unused:UNUSED_PAD src0_sel:WORD_1
	v_pk_mul_f32 v[138:139], v[138:139], s[8:9] op_sel_hi:[1,0]
	s_nop 0
	v_pk_fma_f32 v[40:41], v[40:41], v[172:173], v[138:139]
	v_pk_mul_f32 v[136:137], v[136:137], s[8:9] op_sel_hi:[1,0]
	s_nop 0
	v_pk_fma_f32 v[42:43], v[42:43], v[170:171], v[136:137]
	v_add_u32_e32 v136, v140, v180
	ds_read_b64 v[136:137], v136
	s_waitcnt lgkmcnt(0)
	v_cvt_f32_f16_e32 v138, v136
	v_cvt_f32_f16_sdwa v139, v136 dst_sel:DWORD dst_unused:UNUSED_PAD src0_sel:WORD_1
	v_cvt_f32_f16_e32 v136, v137
	v_cvt_f32_f16_sdwa v137, v137 dst_sel:DWORD dst_unused:UNUSED_PAD src0_sel:WORD_1
	v_pk_mul_f32 v[138:139], v[138:139], s[8:9] op_sel_hi:[1,0]
	s_nop 0
	v_pk_fma_f32 v[36:37], v[36:37], v[168:169], v[138:139]
	v_pk_mul_f32 v[136:137], v[136:137], s[8:9] op_sel_hi:[1,0]
	s_nop 0
	v_pk_fma_f32 v[38:39], v[38:39], v[166:167], v[136:137]
	v_add_u32_e32 v136, v140, v152
	ds_read_b64 v[136:137], v136
	v_pk_add_f32 v[152:153], v[6:7], v[18:19]
	v_pk_add_f32 v[140:141], v[2:3], v[26:27]
	v_pk_mov_b32 v[24:25], v[154:155], v[152:153] op_sel:[1,0]
	v_mov_b32_e32 v26, v154
	s_waitcnt lgkmcnt(0)
	v_cvt_f32_f16_e32 v138, v136
	v_cvt_f32_f16_sdwa v139, v136 dst_sel:DWORD dst_unused:UNUSED_PAD src0_sel:WORD_1
	v_cvt_f32_f16_e32 v136, v137
	v_cvt_f32_f16_sdwa v137, v137 dst_sel:DWORD dst_unused:UNUSED_PAD src0_sel:WORD_1
	v_mov_b32_e32 v27, v153
	v_pk_add_f32 v[18:19], v[8:9], v[144:145]
	v_pk_add_f32 v[24:25], v[24:25], v[26:27]
	v_pk_mov_b32 v[26:27], v[142:143], v[140:141] op_sel:[1,0]
	v_mov_b32_e32 v144, v142
	v_mov_b32_e32 v145, v141
	v_pk_mul_f32 v[138:139], v[138:139], s[8:9] op_sel_hi:[1,0]
	v_pk_mul_f32 v[136:137], v[136:137], s[8:9] op_sel_hi:[1,0]
	v_pk_add_f32 v[26:27], v[26:27], v[144:145]
	v_pk_fma_f32 v[34:35], v[34:35], v[162:163], v[136:137]
	v_pk_fma_f32 v[32:33], v[32:33], v[164:165], v[138:139]
	v_pk_add_f32 v[136:137], v[14:15], v[150:151]
	v_pk_add_f32 v[138:139], v[12:13], v[148:149]
	v_add_f32_e32 v24, v24, v25
	v_pk_add_f32 v[26:27], v[26:27], v[26:27] op_sel_hi:[0,1]
	v_add_f32_e32 v25, 0, v24
	v_add_f32_e32 v145, v138, v139
	v_add_f32_e32 v147, v136, v137
	v_mov_b32_e32 v144, v18
	v_mov_b32_e32 v146, v19
	v_mov_b32_e32 v26, v16
	v_mov_b32_e32 v24, v17
	v_pk_add_f32 v[144:145], v[144:145], v[146:147]
	v_pk_add_f32 v[24:25], v[26:27], v[24:25]
	s_waitcnt lgkmcnt(0)
	s_barrier
	v_pk_add_f32 v[24:25], v[144:145], v[24:25]
	s_nop 0
	v_add_f32_e32 v24, v24, v25
	s_mov_b32 s100, 0xffff0000
	s_mov_b32 s101, 0xffff0000
	s_mov_b32 s98, 0
	s_mov_b32 s99, -1
	v_mov_b32_e32 v25, v24
	v_mov_b32_e32 v210, v24
	s_nop 1
	v_permlane16_swap_b32_e32 v25, v210
	v_cndmask_b32_e64 v25, v210, v25, s[100:101]
	s_waitcnt lgkmcnt(0)
	v_add_f32_e32 v24, v24, v25
	v_mov_b32_e32 v25, v24
	v_mov_b32_e32 v210, v24
	s_nop 1
	v_permlane32_swap_b32_e32 v25, v210
	v_cndmask_b32_e64 v25, v210, v25, s[98:99]
	s_waitcnt lgkmcnt(0)
	v_add_f32_e32 v24, v24, v25
	v_fmamk_f32 v26, v24, 0xbc800000, v153
	v_fmamk_f32 v144, v24, 0xbc800000, v155
	v_fmamk_f32 v25, v24, 0xbc800000, v152
	v_fmamk_f32 v27, v24, 0xbc800000, v154
	v_mul_f32_e32 v144, v144, v144
	v_mul_f32_e32 v26, v26, v26
	v_fmac_f32_e32 v144, v27, v27
	v_fmac_f32_e32 v26, v25, v25
	v_fmamk_f32 v27, v24, 0xbc800000, v141
	v_fmamk_f32 v145, v24, 0xbc800000, v143
	v_add_f32_e32 v25, v144, v26
	v_fmamk_f32 v26, v24, 0xbc800000, v140
	v_fmamk_f32 v144, v24, 0xbc800000, v142
	v_mul_f32_e32 v145, v145, v145
	v_mul_f32_e32 v27, v27, v27
	v_fmac_f32_e32 v145, v144, v144
	v_fmac_f32_e32 v27, v26, v26
	v_add_f32_e32 v26, v145, v27
	v_fmamk_f32 v27, v24, 0xbc800000, v137
	v_fmamk_f32 v145, v24, 0xbc800000, v139
	v_add_f32_e32 v25, v25, v26
	v_fmamk_f32 v26, v24, 0xbc800000, v136
	v_fmamk_f32 v144, v24, 0xbc800000, v138
	v_mul_f32_e32 v145, v145, v145
	v_mul_f32_e32 v27, v27, v27
	v_fmac_f32_e32 v145, v144, v144
	v_fmac_f32_e32 v27, v26, v26
	v_add_f32_e32 v26, v145, v27
	v_fmamk_f32 v27, v24, 0xbc800000, v17
	v_fmamk_f32 v145, v24, 0xbc800000, v19
	v_add_f32_e32 v25, v26, v25
	v_fmamk_f32 v26, v24, 0xbc800000, v16
	v_fmamk_f32 v144, v24, 0xbc800000, v18
	v_mul_f32_e32 v145, v145, v145
	v_mul_f32_e32 v27, v27, v27
	v_fmac_f32_e32 v145, v144, v144
	v_fmac_f32_e32 v27, v26, v26
	v_add_f32_e32 v26, v145, v27
	v_add_f32_e32 v25, v26, v25
	v_mov_b32_e32 v26, v25
	v_mov_b32_e32 v210, v25
	s_nop 1
	v_permlane16_swap_b32_e32 v26, v210
	v_cndmask_b32_e64 v26, v210, v26, s[100:101]
	s_waitcnt lgkmcnt(0)
	v_add_f32_e32 v25, v25, v26
	v_mov_b32_e32 v26, v25
	v_mov_b32_e32 v210, v25
	s_nop 1
	v_permlane32_swap_b32_e32 v26, v210
	v_cndmask_b32_e64 v26, v210, v26, s[98:99]
	s_and_saveexec_b64 s[8:9], vcc
	s_cbranch_execz .LBB0_1005
	s_lshl_b32 s3, s22, 11
	s_add_i32 s3, s12, s3
	v_mul_f32_e32 v24, 0x3c800000, v24
	s_waitcnt lgkmcnt(0)
	v_add_f32_e32 v25, v25, v26
	v_lshl_add_u32 v26, v178, 5, s3
	ds_write_b64 v26, v[24:25]
